# GEMM MFMA blocks accumulator-stationary with snake pair order (k order alternates per accumulator so consecutive MFMAs share an operand)
# speedup vs baseline: 1.0133x; 1.0052x over previous
.LBB0_101:
	ds_read_b128 v[154:157], v151
	ds_read_b128 v[158:161], v151 offset:1024
	ds_read_b128 v[162:165], v151 offset:2048
	ds_read_b128 v[166:169], v151 offset:3072
	ds_read_b128 v[170:173], v152
	ds_read_b128 v[174:177], v152 offset:1024
	ds_read_b128 v[188:191], v152 offset:2048
	ds_read_b128 v[192:195], v152 offset:3072
	s_add_u32 s40, s36, s38
	s_addc_u32 s41, s37, s39
	s_add_u32 s44, s40, 0x100
	s_addc_u32 s45, s41, 0
	s_add_u32 s42, s66, s38
	s_addc_u32 s43, s67, s39
	s_add_u32 s40, s40, 0x180
	s_addc_u32 s41, s41, 0
	s_cmpk_eq_i32 s38, 0x1f00
	s_cselect_b32 s41, s65, s41
	s_cselect_b32 s40, s64, s40
	s_cselect_b32 s43, s35, s43
	s_cselect_b32 s42, s34, s42
	s_cselect_b32 s45, s23, s45
	s_cselect_b32 s44, s22, s44
	s_mov_b32 m0, s57
	v_lshl_add_u64 v[178:179], v[146:147], 0, s[38:39]
	ds_read_b128 v[196:199], v153
	ds_read_b128 v[200:203], v153 offset:1024
	ds_read_b128 v[204:207], v153 offset:2048
	ds_read_b128 v[208:211], v153 offset:3072
	ds_read_b128 v[214:217], v153 offset:4096
	ds_read_b128 v[218:221], v153 offset:5120
	ds_read_b128 v[222:225], v153 offset:6144
	ds_read_b128 v[226:229], v153 offset:7168
	global_load_lds_dwordx4 v[178:179], off
	v_lshl_add_u64 v[178:179], v[148:149], 0, s[38:39]
	s_add_i32 m0, s47, 0xe000
	s_nop 0
	global_load_lds_dwordx4 v[178:179], off
	s_waitcnt vmcnt(8)
	s_waitcnt lgkmcnt(0)
	s_barrier
	s_setprio 1
	s_waitcnt lgkmcnt(0)
	v_mfma_f32_16x16x32_bf16 v[126:129], v[154:157], v[196:199], v[126:129]
	v_mfma_f32_16x16x32_bf16 v[126:129], v[158:161], v[200:203], v[126:129]
	v_mfma_f32_16x16x32_bf16 v[122:125], v[166:169], v[200:203], v[122:125]
	v_mfma_f32_16x16x32_bf16 v[122:125], v[162:165], v[196:199], v[122:125]
	v_mfma_f32_16x16x32_bf16 v[110:113], v[162:165], v[204:207], v[110:113]
	v_mfma_f32_16x16x32_bf16 v[110:113], v[166:169], v[208:211], v[110:113]
	v_mfma_f32_16x16x32_bf16 v[118:121], v[158:161], v[208:211], v[118:121]
	v_mfma_f32_16x16x32_bf16 v[118:121], v[154:157], v[204:207], v[118:121]
	v_mfma_f32_16x16x32_bf16 v[102:105], v[154:157], v[214:217], v[102:105]
	v_mfma_f32_16x16x32_bf16 v[102:105], v[158:161], v[218:221], v[102:105]
	v_mfma_f32_16x16x32_bf16 v[94:97], v[166:169], v[218:221], v[94:97]
	v_mfma_f32_16x16x32_bf16 v[94:97], v[162:165], v[214:217], v[94:97]
	v_mfma_f32_16x16x32_bf16 v[78:81], v[162:165], v[222:225], v[78:81]
	v_mfma_f32_16x16x32_bf16 v[78:81], v[166:169], v[226:229], v[78:81]
	v_mfma_f32_16x16x32_bf16 v[86:89], v[158:161], v[226:229], v[86:89]
	v_mfma_f32_16x16x32_bf16 v[86:89], v[154:157], v[222:225], v[86:89]
	s_setprio 0
	s_setprio 1
	v_mfma_f32_16x16x32_bf16 v[114:117], v[170:173], v[196:199], v[114:117]
	v_mfma_f32_16x16x32_bf16 v[114:117], v[174:177], v[200:203], v[114:117]
	v_mfma_f32_16x16x32_bf16 v[106:109], v[192:195], v[200:203], v[106:109]
	v_mfma_f32_16x16x32_bf16 v[106:109], v[188:191], v[196:199], v[106:109]
	v_mfma_f32_16x16x32_bf16 v[90:93], v[188:191], v[204:207], v[90:93]
	v_mfma_f32_16x16x32_bf16 v[90:93], v[192:195], v[208:211], v[90:93]
	v_mfma_f32_16x16x32_bf16 v[98:101], v[174:177], v[208:211], v[98:101]
	v_mfma_f32_16x16x32_bf16 v[98:101], v[170:173], v[204:207], v[98:101]
	v_mfma_f32_16x16x32_bf16 v[82:85], v[170:173], v[214:217], v[82:85]
	v_mfma_f32_16x16x32_bf16 v[82:85], v[174:177], v[218:221], v[82:85]
	v_mfma_f32_16x16x32_bf16 v[74:77], v[192:195], v[218:221], v[74:77]
	v_mfma_f32_16x16x32_bf16 v[74:77], v[188:191], v[214:217], v[74:77]
	v_mfma_f32_16x16x32_bf16 v[66:69], v[188:191], v[222:225], v[66:69]
	v_mfma_f32_16x16x32_bf16 v[66:69], v[192:195], v[226:229], v[66:69]
	v_mfma_f32_16x16x32_bf16 v[70:73], v[174:177], v[226:229], v[70:73]
	v_mfma_f32_16x16x32_bf16 v[70:73], v[170:173], v[222:225], v[70:73]
	s_setprio 0
	s_barrier
	s_add_i32 s69, s54, s3
	v_lshl_add_u64 v[178:179], s[42:43], 0, v[136:137]
	s_mov_b32 m0, s69
	ds_read_b128 v[196:199], v153 offset:16384
	ds_read_b128 v[200:203], v153 offset:17408
	ds_read_b128 v[204:207], v153 offset:18432
	ds_read_b128 v[208:211], v153 offset:19456
	ds_read_b128 v[214:217], v153 offset:20480
	ds_read_b128 v[218:221], v153 offset:21504
	ds_read_b128 v[222:225], v153 offset:22528
	ds_read_b128 v[226:229], v153 offset:23552
	global_load_lds_dwordx4 v[178:179], off
	s_add_i32 m0, s69, 0x2000
	s_add_u32 s70, s42, 0x108000
	v_lshl_add_u64 v[230:231], s[42:43], 0, v[140:141]
	s_addc_u32 s71, s43, 0
	s_add_i32 s69, s55, s3
	global_load_lds_dwordx4 v[230:231], off
	v_lshl_add_u64 v[232:233], s[70:71], 0, v[136:137]
	s_mov_b32 m0, s69
	s_nop 0
	global_load_lds_dwordx4 v[232:233], off
	v_lshl_add_u64 v[232:233], s[70:71], 0, v[140:141]
	s_add_i32 m0, s69, 0x2000
	s_nop 0
	global_load_lds_dwordx4 v[232:233], off
	v_lshl_add_u64 v[232:233], s[44:45], 0, v[134:135]
	s_mov_b32 m0, s47
	s_nop 0
	global_load_lds_dwordx4 v[232:233], off
	v_lshl_add_u64 v[232:233], s[44:45], 0, v[138:139]
	s_mov_b32 m0, s48
	s_nop 0
	global_load_lds_dwordx4 v[232:233], off
	s_waitcnt vmcnt(8)
	s_waitcnt lgkmcnt(0)
	s_barrier
	s_setprio 1
	s_waitcnt lgkmcnt(0)
	v_mfma_f32_16x16x32_bf16 v[62:65], v[154:157], v[196:199], v[62:65]
	v_mfma_f32_16x16x32_bf16 v[62:65], v[158:161], v[200:203], v[62:65]
	v_mfma_f32_16x16x32_bf16 v[58:61], v[166:169], v[200:203], v[58:61]
	v_mfma_f32_16x16x32_bf16 v[58:61], v[162:165], v[196:199], v[58:61]
	v_mfma_f32_16x16x32_bf16 v[46:49], v[162:165], v[204:207], v[46:49]
	v_mfma_f32_16x16x32_bf16 v[46:49], v[166:169], v[208:211], v[46:49]
	v_mfma_f32_16x16x32_bf16 v[54:57], v[158:161], v[208:211], v[54:57]
	v_mfma_f32_16x16x32_bf16 v[54:57], v[154:157], v[204:207], v[54:57]
	v_mfma_f32_16x16x32_bf16 v[38:41], v[154:157], v[214:217], v[38:41]
	v_mfma_f32_16x16x32_bf16 v[38:41], v[158:161], v[218:221], v[38:41]
	v_mfma_f32_16x16x32_bf16 v[30:33], v[166:169], v[218:221], v[30:33]
	v_mfma_f32_16x16x32_bf16 v[30:33], v[162:165], v[214:217], v[30:33]
	v_mfma_f32_16x16x32_bf16 v[14:17], v[162:165], v[222:225], v[14:17]
	v_mfma_f32_16x16x32_bf16 v[14:17], v[166:169], v[226:229], v[14:17]
	v_mfma_f32_16x16x32_bf16 v[22:25], v[158:161], v[226:229], v[22:25]
	v_mfma_f32_16x16x32_bf16 v[22:25], v[154:157], v[222:225], v[22:25]
	s_setprio 0
	s_setprio 1
	v_mfma_f32_16x16x32_bf16 v[50:53], v[170:173], v[196:199], v[50:53]
	v_mfma_f32_16x16x32_bf16 v[50:53], v[174:177], v[200:203], v[50:53]
	v_mfma_f32_16x16x32_bf16 v[42:45], v[192:195], v[200:203], v[42:45]
	v_mfma_f32_16x16x32_bf16 v[42:45], v[188:191], v[196:199], v[42:45]
	v_mfma_f32_16x16x32_bf16 v[26:29], v[188:191], v[204:207], v[26:29]
	v_mfma_f32_16x16x32_bf16 v[26:29], v[192:195], v[208:211], v[26:29]
	v_mfma_f32_16x16x32_bf16 v[34:37], v[174:177], v[208:211], v[34:37]
	v_mfma_f32_16x16x32_bf16 v[34:37], v[170:173], v[204:207], v[34:37]
	v_mfma_f32_16x16x32_bf16 v[18:21], v[170:173], v[214:217], v[18:21]
	v_mfma_f32_16x16x32_bf16 v[18:21], v[174:177], v[218:221], v[18:21]
	v_mfma_f32_16x16x32_bf16 v[10:13], v[192:195], v[218:221], v[10:13]
	v_mfma_f32_16x16x32_bf16 v[10:13], v[188:191], v[214:217], v[10:13]
	v_mfma_f32_16x16x32_bf16 v[2:5], v[188:191], v[222:225], v[2:5]
	v_mfma_f32_16x16x32_bf16 v[2:5], v[192:195], v[226:229], v[2:5]
	v_mfma_f32_16x16x32_bf16 v[6:9], v[174:177], v[226:229], v[6:9]
	v_mfma_f32_16x16x32_bf16 v[6:9], v[170:173], v[222:225], v[6:9]
	s_setprio 0
	s_barrier
	s_add_i32 s69, 0, 0x18000
	s_add_i32 s70, 0, 0x1c000
	v_add_u32_e32 v166, s69, v133
	v_add_u32_e32 v187, s70, v133
	ds_read_b128 v[154:157], v166
	ds_read_b128 v[158:161], v166 offset:1024
	ds_read_b128 v[162:165], v166 offset:2048
	ds_read_b128 v[166:169], v166 offset:3072
	ds_read_b128 v[170:173], v187
	ds_read_b128 v[174:177], v187 offset:1024
	ds_read_b128 v[188:191], v187 offset:2048
	ds_read_b128 v[192:195], v187 offset:3072
	s_add_u32 s44, s44, 0x108000
	s_addc_u32 s45, s45, 0
	s_mov_b32 m0, s49
	v_lshl_add_u64 v[232:233], s[44:45], 0, v[134:135]
	ds_read_b128 v[196:199], v153 offset:32768
	ds_read_b128 v[200:203], v153 offset:33792
	ds_read_b128 v[204:207], v153 offset:34816
	ds_read_b128 v[208:211], v153 offset:35840
	ds_read_b128 v[214:217], v153 offset:36864
	ds_read_b128 v[218:221], v153 offset:37888
	ds_read_b128 v[222:225], v153 offset:38912
	ds_read_b128 v[226:229], v153 offset:39936
	global_load_lds_dwordx4 v[232:233], off
	v_lshl_add_u64 v[232:233], s[44:45], 0, v[138:139]
	s_mov_b32 m0, s50
	s_nop 0
	global_load_lds_dwordx4 v[232:233], off
	s_waitcnt vmcnt(8)
	s_waitcnt lgkmcnt(0)
	s_barrier
	s_setprio 1
	s_waitcnt lgkmcnt(0)
	v_mfma_f32_16x16x32_bf16 v[126:129], v[154:157], v[196:199], v[126:129]
	v_mfma_f32_16x16x32_bf16 v[126:129], v[158:161], v[200:203], v[126:129]
	v_mfma_f32_16x16x32_bf16 v[122:125], v[166:169], v[200:203], v[122:125]
	v_mfma_f32_16x16x32_bf16 v[122:125], v[162:165], v[196:199], v[122:125]
	v_mfma_f32_16x16x32_bf16 v[110:113], v[162:165], v[204:207], v[110:113]
	v_mfma_f32_16x16x32_bf16 v[110:113], v[166:169], v[208:211], v[110:113]
	v_mfma_f32_16x16x32_bf16 v[118:121], v[158:161], v[208:211], v[118:121]
	v_mfma_f32_16x16x32_bf16 v[118:121], v[154:157], v[204:207], v[118:121]
	v_mfma_f32_16x16x32_bf16 v[102:105], v[154:157], v[214:217], v[102:105]
	v_mfma_f32_16x16x32_bf16 v[102:105], v[158:161], v[218:221], v[102:105]
	v_mfma_f32_16x16x32_bf16 v[94:97], v[166:169], v[218:221], v[94:97]
	v_mfma_f32_16x16x32_bf16 v[94:97], v[162:165], v[214:217], v[94:97]
	v_mfma_f32_16x16x32_bf16 v[78:81], v[162:165], v[222:225], v[78:81]
	v_mfma_f32_16x16x32_bf16 v[78:81], v[166:169], v[226:229], v[78:81]
	v_mfma_f32_16x16x32_bf16 v[86:89], v[158:161], v[226:229], v[86:89]
	v_mfma_f32_16x16x32_bf16 v[86:89], v[154:157], v[222:225], v[86:89]
	s_setprio 0
	s_setprio 1
	v_mfma_f32_16x16x32_bf16 v[114:117], v[170:173], v[196:199], v[114:117]
	v_mfma_f32_16x16x32_bf16 v[114:117], v[174:177], v[200:203], v[114:117]
	v_mfma_f32_16x16x32_bf16 v[106:109], v[192:195], v[200:203], v[106:109]
	v_mfma_f32_16x16x32_bf16 v[106:109], v[188:191], v[196:199], v[106:109]
	v_mfma_f32_16x16x32_bf16 v[90:93], v[188:191], v[204:207], v[90:93]
	v_mfma_f32_16x16x32_bf16 v[90:93], v[192:195], v[208:211], v[90:93]
	v_mfma_f32_16x16x32_bf16 v[98:101], v[174:177], v[208:211], v[98:101]
	v_mfma_f32_16x16x32_bf16 v[98:101], v[170:173], v[204:207], v[98:101]
	v_mfma_f32_16x16x32_bf16 v[82:85], v[170:173], v[214:217], v[82:85]
	v_mfma_f32_16x16x32_bf16 v[82:85], v[174:177], v[218:221], v[82:85]
	v_mfma_f32_16x16x32_bf16 v[74:77], v[192:195], v[218:221], v[74:77]
	v_mfma_f32_16x16x32_bf16 v[74:77], v[188:191], v[214:217], v[74:77]
	v_mfma_f32_16x16x32_bf16 v[66:69], v[188:191], v[222:225], v[66:69]
	v_mfma_f32_16x16x32_bf16 v[66:69], v[192:195], v[226:229], v[66:69]
	v_mfma_f32_16x16x32_bf16 v[70:73], v[174:177], v[226:229], v[70:73]
	v_mfma_f32_16x16x32_bf16 v[70:73], v[170:173], v[222:225], v[70:73]
	s_setprio 0
	s_barrier
	s_add_i32 s44, s69, s3
	v_lshl_add_u64 v[178:179], v[178:179], 0, s[12:13]
	s_mov_b32 m0, s44
	ds_read_b128 v[196:199], v153 offset:49152
	ds_read_b128 v[200:203], v153 offset:50176
	ds_read_b128 v[204:207], v153 offset:51200
	ds_read_b128 v[208:211], v153 offset:52224
	ds_read_b128 v[214:217], v153 offset:53248
	ds_read_b128 v[218:221], v153 offset:54272
	ds_read_b128 v[222:225], v153 offset:55296
	ds_read_b128 v[226:229], v153 offset:56320
	global_load_lds_dwordx4 v[178:179], off
	s_add_i32 m0, s44, 0x2000
	s_add_u32 s42, s42, 0x108080
	v_lshl_add_u64 v[178:179], v[230:231], 0, s[12:13]
	s_addc_u32 s43, s43, 0
	s_add_i32 s44, s70, s3
	global_load_lds_dwordx4 v[178:179], off
	v_lshl_add_u64 v[178:179], s[42:43], 0, v[136:137]
	s_mov_b32 m0, s44
	s_nop 0
	global_load_lds_dwordx4 v[178:179], off
	v_lshl_add_u64 v[178:179], s[42:43], 0, v[140:141]
	s_add_i32 m0, s44, 0x2000
	s_nop 0
	global_load_lds_dwordx4 v[178:179], off
	v_lshl_add_u64 v[178:179], s[40:41], 0, v[134:135]
	s_mov_b32 m0, s52
	s_nop 0
	global_load_lds_dwordx4 v[178:179], off
	v_lshl_add_u64 v[178:179], s[40:41], 0, v[138:139]
	s_mov_b32 m0, s53
	s_nop 0
	global_load_lds_dwordx4 v[178:179], off
	s_waitcnt vmcnt(8)
	s_waitcnt lgkmcnt(0)
	s_barrier
	s_setprio 1
	s_waitcnt lgkmcnt(0)
	v_mfma_f32_16x16x32_bf16 v[62:65], v[154:157], v[196:199], v[62:65]
	v_mfma_f32_16x16x32_bf16 v[62:65], v[158:161], v[200:203], v[62:65]
	v_mfma_f32_16x16x32_bf16 v[58:61], v[166:169], v[200:203], v[58:61]
	v_mfma_f32_16x16x32_bf16 v[58:61], v[162:165], v[196:199], v[58:61]
	v_mfma_f32_16x16x32_bf16 v[46:49], v[162:165], v[204:207], v[46:49]
	v_mfma_f32_16x16x32_bf16 v[46:49], v[166:169], v[208:211], v[46:49]
	v_mfma_f32_16x16x32_bf16 v[54:57], v[158:161], v[208:211], v[54:57]
	v_mfma_f32_16x16x32_bf16 v[54:57], v[154:157], v[204:207], v[54:57]
	v_mfma_f32_16x16x32_bf16 v[38:41], v[154:157], v[214:217], v[38:41]
	v_mfma_f32_16x16x32_bf16 v[38:41], v[158:161], v[218:221], v[38:41]
	v_mfma_f32_16x16x32_bf16 v[30:33], v[166:169], v[218:221], v[30:33]
	v_mfma_f32_16x16x32_bf16 v[30:33], v[162:165], v[214:217], v[30:33]
	v_mfma_f32_16x16x32_bf16 v[14:17], v[162:165], v[222:225], v[14:17]
	v_mfma_f32_16x16x32_bf16 v[14:17], v[166:169], v[226:229], v[14:17]
	v_mfma_f32_16x16x32_bf16 v[22:25], v[158:161], v[226:229], v[22:25]
	v_mfma_f32_16x16x32_bf16 v[22:25], v[154:157], v[222:225], v[22:25]
	s_setprio 0
	s_setprio 1
	v_mfma_f32_16x16x32_bf16 v[50:53], v[170:173], v[196:199], v[50:53]
	v_mfma_f32_16x16x32_bf16 v[50:53], v[174:177], v[200:203], v[50:53]
	v_mfma_f32_16x16x32_bf16 v[42:45], v[192:195], v[200:203], v[42:45]
	v_mfma_f32_16x16x32_bf16 v[42:45], v[188:191], v[196:199], v[42:45]
	v_mfma_f32_16x16x32_bf16 v[26:29], v[188:191], v[204:207], v[26:29]
	v_mfma_f32_16x16x32_bf16 v[26:29], v[192:195], v[208:211], v[26:29]
	v_mfma_f32_16x16x32_bf16 v[34:37], v[174:177], v[208:211], v[34:37]
	v_mfma_f32_16x16x32_bf16 v[34:37], v[170:173], v[204:207], v[34:37]
	v_mfma_f32_16x16x32_bf16 v[18:21], v[170:173], v[214:217], v[18:21]
	v_mfma_f32_16x16x32_bf16 v[18:21], v[174:177], v[218:221], v[18:21]
	v_mfma_f32_16x16x32_bf16 v[10:13], v[192:195], v[218:221], v[10:13]
	v_mfma_f32_16x16x32_bf16 v[10:13], v[188:191], v[214:217], v[10:13]
	v_mfma_f32_16x16x32_bf16 v[2:5], v[188:191], v[222:225], v[2:5]
	v_mfma_f32_16x16x32_bf16 v[2:5], v[192:195], v[226:229], v[2:5]
	v_mfma_f32_16x16x32_bf16 v[6:9], v[174:177], v[226:229], v[6:9]
	v_mfma_f32_16x16x32_bf16 v[6:9], v[170:173], v[222:225], v[6:9]
	s_setprio 0
	s_barrier
	s_add_i32 s68, s68, 2
	s_add_u32 s38, s38, 0x100
	s_addc_u32 s39, s39, 0
	s_cmp_gt_u32 s68, 61
	s_cbranch_scc0 .LBB0_101
	s_and_b64 vcc, exec, s[20:21]
	s_cbranch_vccz .LBB0_104
	s_barrier

.LBB0_235:
	ds_read_b128 v[156:159], v150
	ds_read_b128 v[160:163], v150 offset:1024
	ds_read_b128 v[164:167], v150 offset:2048
	ds_read_b128 v[168:171], v150 offset:3072
	ds_read_b128 v[172:175], v151
	ds_read_b128 v[176:179], v151 offset:1024
	ds_read_b128 v[180:183], v151 offset:2048
	ds_read_b128 v[184:187], v151 offset:3072
	s_add_u32 s36, s4, s34
	s_addc_u32 s37, s5, s35
	s_add_u32 s40, s36, 0x100
	s_addc_u32 s41, s37, 0
	s_add_u32 s38, s62, s34
	s_addc_u32 s39, s63, s35
	s_add_u32 s36, s36, 0x180
	s_addc_u32 s37, s37, 0
	s_cmpk_eq_i32 s34, 0x1f00
	s_cselect_b32 s37, s61, s37
	s_cselect_b32 s36, s60, s36
	s_cselect_b32 s39, s31, s39
	s_cselect_b32 s38, s30, s38
	s_cselect_b32 s41, s23, s41
	s_cselect_b32 s40, s22, s40
	s_mov_b32 m0, s46
	v_lshl_add_u64 v[222:223], v[146:147], 0, s[34:35]
	ds_read_b128 v[188:191], v152
	ds_read_b128 v[192:195], v152 offset:1024
	ds_read_b128 v[196:199], v152 offset:2048
	ds_read_b128 v[200:203], v152 offset:3072
	ds_read_b128 v[204:207], v152 offset:4096
	ds_read_b128 v[208:211], v152 offset:5120
	ds_read_b128 v[214:217], v152 offset:6144
	ds_read_b128 v[218:221], v152 offset:7168
	global_load_lds_dwordx4 v[222:223], off
	v_lshl_add_u64 v[222:223], v[148:149], 0, s[34:35]
	s_mov_b32 m0, s47
	s_nop 0
	global_load_lds_dwordx4 v[222:223], off
	s_waitcnt vmcnt(8)
	s_waitcnt lgkmcnt(0)
	s_barrier
	s_setprio 1
	s_waitcnt lgkmcnt(0)
	v_mfma_f32_16x16x32_bf16 v[126:129], v[156:159], v[188:191], v[126:129]
	v_mfma_f32_16x16x32_bf16 v[126:129], v[160:163], v[192:195], v[126:129]
	v_mfma_f32_16x16x32_bf16 v[122:125], v[168:171], v[192:195], v[122:125]
	v_mfma_f32_16x16x32_bf16 v[122:125], v[164:167], v[188:191], v[122:125]
	v_mfma_f32_16x16x32_bf16 v[106:109], v[164:167], v[196:199], v[106:109]
	v_mfma_f32_16x16x32_bf16 v[106:109], v[168:171], v[200:203], v[106:109]
	v_mfma_f32_16x16x32_bf16 v[110:113], v[160:163], v[200:203], v[110:113]
	v_mfma_f32_16x16x32_bf16 v[110:113], v[156:159], v[196:199], v[110:113]
	v_mfma_f32_16x16x32_bf16 v[94:97], v[156:159], v[204:207], v[94:97]
	v_mfma_f32_16x16x32_bf16 v[94:97], v[160:163], v[208:211], v[94:97]
	v_mfma_f32_16x16x32_bf16 v[90:93], v[168:171], v[208:211], v[90:93]
	v_mfma_f32_16x16x32_bf16 v[90:93], v[164:167], v[204:207], v[90:93]
	v_mfma_f32_16x16x32_bf16 v[74:77], v[164:167], v[214:217], v[74:77]
	v_mfma_f32_16x16x32_bf16 v[74:77], v[168:171], v[218:221], v[74:77]
	v_mfma_f32_16x16x32_bf16 v[78:81], v[160:163], v[218:221], v[78:81]
	v_mfma_f32_16x16x32_bf16 v[78:81], v[156:159], v[214:217], v[78:81]
	s_setprio 0
	s_setprio 1
	v_mfma_f32_16x16x32_bf16 v[118:121], v[172:175], v[188:191], v[118:121]
	v_mfma_f32_16x16x32_bf16 v[118:121], v[176:179], v[192:195], v[118:121]
	v_mfma_f32_16x16x32_bf16 v[114:117], v[184:187], v[192:195], v[114:117]
	v_mfma_f32_16x16x32_bf16 v[114:117], v[180:183], v[188:191], v[114:117]
	v_mfma_f32_16x16x32_bf16 v[98:101], v[180:183], v[196:199], v[98:101]
	v_mfma_f32_16x16x32_bf16 v[98:101], v[184:187], v[200:203], v[98:101]
	v_mfma_f32_16x16x32_bf16 v[102:105], v[176:179], v[200:203], v[102:105]
	v_mfma_f32_16x16x32_bf16 v[102:105], v[172:175], v[196:199], v[102:105]
	v_mfma_f32_16x16x32_bf16 v[86:89], v[172:175], v[204:207], v[86:89]
	v_mfma_f32_16x16x32_bf16 v[86:89], v[176:179], v[208:211], v[86:89]
	v_mfma_f32_16x16x32_bf16 v[82:85], v[184:187], v[208:211], v[82:85]
	v_mfma_f32_16x16x32_bf16 v[82:85], v[180:183], v[204:207], v[82:85]
	v_mfma_f32_16x16x32_bf16 v[66:69], v[180:183], v[214:217], v[66:69]
	v_mfma_f32_16x16x32_bf16 v[66:69], v[184:187], v[218:221], v[66:69]
	v_mfma_f32_16x16x32_bf16 v[70:73], v[176:179], v[218:221], v[70:73]
	v_mfma_f32_16x16x32_bf16 v[70:73], v[172:175], v[214:217], v[70:73]
	s_setprio 0
	s_barrier
	s_mov_b32 m0, s48
	v_lshl_add_u64 v[222:223], s[38:39], 0, v[132:133]
	s_add_u32 s66, s38, 0x108000
	ds_read_b128 v[188:191], v152 offset:16384
	ds_read_b128 v[192:195], v152 offset:17408
	ds_read_b128 v[196:199], v152 offset:18432
	ds_read_b128 v[200:203], v152 offset:19456
	ds_read_b128 v[204:207], v152 offset:20480
	ds_read_b128 v[208:211], v152 offset:21504
	ds_read_b128 v[214:217], v152 offset:22528
	ds_read_b128 v[218:221], v152 offset:23552
	global_load_lds_dwordx4 v[222:223], off
	v_lshl_add_u64 v[224:225], s[38:39], 0, v[136:137]
	s_mov_b32 m0, s49
	s_addc_u32 s67, s39, 0
	global_load_lds_dwordx4 v[224:225], off
	v_lshl_add_u64 v[226:227], s[66:67], 0, v[132:133]
	s_mov_b32 m0, s50
	s_nop 0
	global_load_lds_dwordx4 v[226:227], off
	v_lshl_add_u64 v[226:227], s[66:67], 0, v[136:137]
	s_mov_b32 m0, s51
	s_nop 0
	global_load_lds_dwordx4 v[226:227], off
	v_lshl_add_u64 v[226:227], s[40:41], 0, v[130:131]
	s_mov_b32 m0, s3
	s_nop 0
	global_load_lds_dwordx4 v[226:227], off
	v_lshl_add_u64 v[226:227], s[40:41], 0, v[134:135]
	s_mov_b32 m0, s33
	s_nop 0
	global_load_lds_dwordx4 v[226:227], off
	s_waitcnt vmcnt(8)
	s_waitcnt lgkmcnt(0)
	s_barrier
	s_setprio 1
	s_waitcnt lgkmcnt(0)
	v_mfma_f32_16x16x32_bf16 v[62:65], v[156:159], v[188:191], v[62:65]
	v_mfma_f32_16x16x32_bf16 v[62:65], v[160:163], v[192:195], v[62:65]
	v_mfma_f32_16x16x32_bf16 v[58:61], v[168:171], v[192:195], v[58:61]
	v_mfma_f32_16x16x32_bf16 v[58:61], v[164:167], v[188:191], v[58:61]
	v_mfma_f32_16x16x32_bf16 v[42:45], v[164:167], v[196:199], v[42:45]
	v_mfma_f32_16x16x32_bf16 v[42:45], v[168:171], v[200:203], v[42:45]
	v_mfma_f32_16x16x32_bf16 v[46:49], v[160:163], v[200:203], v[46:49]
	v_mfma_f32_16x16x32_bf16 v[46:49], v[156:159], v[196:199], v[46:49]
	v_mfma_f32_16x16x32_bf16 v[30:33], v[156:159], v[204:207], v[30:33]
	v_mfma_f32_16x16x32_bf16 v[30:33], v[160:163], v[208:211], v[30:33]
	v_mfma_f32_16x16x32_bf16 v[26:29], v[168:171], v[208:211], v[26:29]
	v_mfma_f32_16x16x32_bf16 v[26:29], v[164:167], v[204:207], v[26:29]
	v_mfma_f32_16x16x32_bf16 v[10:13], v[164:167], v[214:217], v[10:13]
	v_mfma_f32_16x16x32_bf16 v[10:13], v[168:171], v[218:221], v[10:13]
	v_mfma_f32_16x16x32_bf16 v[14:17], v[160:163], v[218:221], v[14:17]
	v_mfma_f32_16x16x32_bf16 v[14:17], v[156:159], v[214:217], v[14:17]
	s_setprio 0
	s_setprio 1
	v_mfma_f32_16x16x32_bf16 v[54:57], v[172:175], v[188:191], v[54:57]
	v_mfma_f32_16x16x32_bf16 v[54:57], v[176:179], v[192:195], v[54:57]
	v_mfma_f32_16x16x32_bf16 v[50:53], v[184:187], v[192:195], v[50:53]
	v_mfma_f32_16x16x32_bf16 v[50:53], v[180:183], v[188:191], v[50:53]
	v_mfma_f32_16x16x32_bf16 v[34:37], v[180:183], v[196:199], v[34:37]
	v_mfma_f32_16x16x32_bf16 v[34:37], v[184:187], v[200:203], v[34:37]
	v_mfma_f32_16x16x32_bf16 v[38:41], v[176:179], v[200:203], v[38:41]
	v_mfma_f32_16x16x32_bf16 v[38:41], v[172:175], v[196:199], v[38:41]
	v_mfma_f32_16x16x32_bf16 v[22:25], v[172:175], v[204:207], v[22:25]
	v_mfma_f32_16x16x32_bf16 v[22:25], v[176:179], v[208:211], v[22:25]
	v_mfma_f32_16x16x32_bf16 v[18:21], v[184:187], v[208:211], v[18:21]
	v_mfma_f32_16x16x32_bf16 v[18:21], v[180:183], v[204:207], v[18:21]
	v_mfma_f32_16x16x32_bf16 v[2:5], v[180:183], v[214:217], v[2:5]
	v_mfma_f32_16x16x32_bf16 v[2:5], v[184:187], v[218:221], v[2:5]
	v_mfma_f32_16x16x32_bf16 v[6:9], v[176:179], v[218:221], v[6:9]
	v_mfma_f32_16x16x32_bf16 v[6:9], v[172:175], v[214:217], v[6:9]
	s_setprio 0
	s_barrier
	ds_read_b128 v[156:159], v153
	ds_read_b128 v[160:163], v153 offset:1024
	ds_read_b128 v[164:167], v153 offset:2048
	ds_read_b128 v[168:171], v153 offset:3072
	ds_read_b128 v[172:175], v154
	ds_read_b128 v[176:179], v154 offset:1024
	ds_read_b128 v[180:183], v154 offset:2048
	ds_read_b128 v[184:187], v154 offset:3072
	s_add_u32 s40, s40, 0x108000
	s_addc_u32 s41, s41, 0
	s_mov_b32 m0, s42
	v_lshl_add_u64 v[226:227], s[40:41], 0, v[130:131]
	ds_read_b128 v[188:191], v152 offset:32768
	ds_read_b128 v[192:195], v152 offset:33792
	ds_read_b128 v[196:199], v152 offset:34816
	ds_read_b128 v[200:203], v152 offset:35840
	ds_read_b128 v[204:207], v152 offset:36864
	ds_read_b128 v[208:211], v152 offset:37888
	ds_read_b128 v[214:217], v152 offset:38912
	ds_read_b128 v[218:221], v152 offset:39936
	global_load_lds_dwordx4 v[226:227], off
	v_lshl_add_u64 v[226:227], s[40:41], 0, v[134:135]
	s_mov_b32 m0, s43
	s_nop 0
	global_load_lds_dwordx4 v[226:227], off
	s_waitcnt vmcnt(8)
	s_waitcnt lgkmcnt(0)
	s_barrier
	s_setprio 1
	s_waitcnt lgkmcnt(0)
	v_mfma_f32_16x16x32_bf16 v[126:129], v[156:159], v[188:191], v[126:129]
	v_mfma_f32_16x16x32_bf16 v[126:129], v[160:163], v[192:195], v[126:129]
	v_mfma_f32_16x16x32_bf16 v[122:125], v[168:171], v[192:195], v[122:125]
	v_mfma_f32_16x16x32_bf16 v[122:125], v[164:167], v[188:191], v[122:125]
	v_mfma_f32_16x16x32_bf16 v[106:109], v[164:167], v[196:199], v[106:109]
	v_mfma_f32_16x16x32_bf16 v[106:109], v[168:171], v[200:203], v[106:109]
	v_mfma_f32_16x16x32_bf16 v[110:113], v[160:163], v[200:203], v[110:113]
	v_mfma_f32_16x16x32_bf16 v[110:113], v[156:159], v[196:199], v[110:113]
	v_mfma_f32_16x16x32_bf16 v[94:97], v[156:159], v[204:207], v[94:97]
	v_mfma_f32_16x16x32_bf16 v[94:97], v[160:163], v[208:211], v[94:97]
	v_mfma_f32_16x16x32_bf16 v[90:93], v[168:171], v[208:211], v[90:93]
	v_mfma_f32_16x16x32_bf16 v[90:93], v[164:167], v[204:207], v[90:93]
	v_mfma_f32_16x16x32_bf16 v[74:77], v[164:167], v[214:217], v[74:77]
	v_mfma_f32_16x16x32_bf16 v[74:77], v[168:171], v[218:221], v[74:77]
	v_mfma_f32_16x16x32_bf16 v[78:81], v[160:163], v[218:221], v[78:81]
	v_mfma_f32_16x16x32_bf16 v[78:81], v[156:159], v[214:217], v[78:81]
	s_setprio 0
	s_setprio 1
	v_mfma_f32_16x16x32_bf16 v[118:121], v[172:175], v[188:191], v[118:121]
	v_mfma_f32_16x16x32_bf16 v[118:121], v[176:179], v[192:195], v[118:121]
	v_mfma_f32_16x16x32_bf16 v[114:117], v[184:187], v[192:195], v[114:117]
	v_mfma_f32_16x16x32_bf16 v[114:117], v[180:183], v[188:191], v[114:117]
	v_mfma_f32_16x16x32_bf16 v[98:101], v[180:183], v[196:199], v[98:101]
	v_mfma_f32_16x16x32_bf16 v[98:101], v[184:187], v[200:203], v[98:101]
	v_mfma_f32_16x16x32_bf16 v[102:105], v[176:179], v[200:203], v[102:105]
	v_mfma_f32_16x16x32_bf16 v[102:105], v[172:175], v[196:199], v[102:105]
	v_mfma_f32_16x16x32_bf16 v[86:89], v[172:175], v[204:207], v[86:89]
	v_mfma_f32_16x16x32_bf16 v[86:89], v[176:179], v[208:211], v[86:89]
	v_mfma_f32_16x16x32_bf16 v[82:85], v[184:187], v[208:211], v[82:85]
	v_mfma_f32_16x16x32_bf16 v[82:85], v[180:183], v[204:207], v[82:85]
	v_mfma_f32_16x16x32_bf16 v[66:69], v[180:183], v[214:217], v[66:69]
	v_mfma_f32_16x16x32_bf16 v[66:69], v[184:187], v[218:221], v[66:69]
	v_mfma_f32_16x16x32_bf16 v[70:73], v[176:179], v[218:221], v[70:73]
	v_mfma_f32_16x16x32_bf16 v[70:73], v[172:175], v[214:217], v[70:73]
	s_setprio 0
	s_barrier
	s_mov_b32 m0, s53
	v_lshl_add_u64 v[222:223], v[222:223], 0, s[16:17]
	s_add_u32 s38, s38, 0x108080
	ds_read_b128 v[188:191], v152 offset:49152
	ds_read_b128 v[192:195], v152 offset:50176
	ds_read_b128 v[196:199], v152 offset:51200
	ds_read_b128 v[200:203], v152 offset:52224
	ds_read_b128 v[204:207], v152 offset:53248
	ds_read_b128 v[208:211], v152 offset:54272
	ds_read_b128 v[214:217], v152 offset:55296
	ds_read_b128 v[218:221], v152 offset:56320
	global_load_lds_dwordx4 v[222:223], off
	v_lshl_add_u64 v[222:223], v[224:225], 0, s[16:17]
	s_mov_b32 m0, s54
	s_addc_u32 s39, s39, 0
	s_add_i32 s40, s52, s2
	global_load_lds_dwordx4 v[222:223], off
	v_lshl_add_u64 v[222:223], s[38:39], 0, v[132:133]
	s_mov_b32 m0, s40
	s_nop 0
	global_load_lds_dwordx4 v[222:223], off
	v_lshl_add_u64 v[222:223], s[38:39], 0, v[136:137]
	s_add_i32 m0, s40, 0x2000
	s_nop 0
	global_load_lds_dwordx4 v[222:223], off
	v_lshl_add_u64 v[222:223], s[36:37], 0, v[130:131]
	s_mov_b32 m0, s44
	s_nop 0
	global_load_lds_dwordx4 v[222:223], off
	v_lshl_add_u64 v[222:223], s[36:37], 0, v[134:135]
	s_mov_b32 m0, s45
	s_nop 0
	global_load_lds_dwordx4 v[222:223], off
	s_waitcnt vmcnt(8)
	s_waitcnt lgkmcnt(0)
	s_barrier
	s_setprio 1
	s_waitcnt lgkmcnt(0)
	v_mfma_f32_16x16x32_bf16 v[62:65], v[156:159], v[188:191], v[62:65]
	v_mfma_f32_16x16x32_bf16 v[62:65], v[160:163], v[192:195], v[62:65]
	v_mfma_f32_16x16x32_bf16 v[58:61], v[168:171], v[192:195], v[58:61]
	v_mfma_f32_16x16x32_bf16 v[58:61], v[164:167], v[188:191], v[58:61]
	v_mfma_f32_16x16x32_bf16 v[42:45], v[164:167], v[196:199], v[42:45]
	v_mfma_f32_16x16x32_bf16 v[42:45], v[168:171], v[200:203], v[42:45]
	v_mfma_f32_16x16x32_bf16 v[46:49], v[160:163], v[200:203], v[46:49]
	v_mfma_f32_16x16x32_bf16 v[46:49], v[156:159], v[196:199], v[46:49]
	v_mfma_f32_16x16x32_bf16 v[30:33], v[156:159], v[204:207], v[30:33]
	v_mfma_f32_16x16x32_bf16 v[30:33], v[160:163], v[208:211], v[30:33]
	v_mfma_f32_16x16x32_bf16 v[26:29], v[168:171], v[208:211], v[26:29]
	v_mfma_f32_16x16x32_bf16 v[26:29], v[164:167], v[204:207], v[26:29]
	v_mfma_f32_16x16x32_bf16 v[10:13], v[164:167], v[214:217], v[10:13]
	v_mfma_f32_16x16x32_bf16 v[10:13], v[168:171], v[218:221], v[10:13]
	v_mfma_f32_16x16x32_bf16 v[14:17], v[160:163], v[218:221], v[14:17]
	v_mfma_f32_16x16x32_bf16 v[14:17], v[156:159], v[214:217], v[14:17]
	s_setprio 0
	s_setprio 1
	v_mfma_f32_16x16x32_bf16 v[54:57], v[172:175], v[188:191], v[54:57]
	v_mfma_f32_16x16x32_bf16 v[54:57], v[176:179], v[192:195], v[54:57]
	v_mfma_f32_16x16x32_bf16 v[50:53], v[184:187], v[192:195], v[50:53]
	v_mfma_f32_16x16x32_bf16 v[50:53], v[180:183], v[188:191], v[50:53]
	v_mfma_f32_16x16x32_bf16 v[34:37], v[180:183], v[196:199], v[34:37]
	v_mfma_f32_16x16x32_bf16 v[34:37], v[184:187], v[200:203], v[34:37]
	v_mfma_f32_16x16x32_bf16 v[38:41], v[176:179], v[200:203], v[38:41]
	v_mfma_f32_16x16x32_bf16 v[38:41], v[172:175], v[196:199], v[38:41]
	v_mfma_f32_16x16x32_bf16 v[22:25], v[172:175], v[204:207], v[22:25]
	v_mfma_f32_16x16x32_bf16 v[22:25], v[176:179], v[208:211], v[22:25]
	v_mfma_f32_16x16x32_bf16 v[18:21], v[184:187], v[208:211], v[18:21]
	v_mfma_f32_16x16x32_bf16 v[18:21], v[180:183], v[204:207], v[18:21]
	v_mfma_f32_16x16x32_bf16 v[2:5], v[180:183], v[214:217], v[2:5]
	v_mfma_f32_16x16x32_bf16 v[2:5], v[184:187], v[218:221], v[2:5]
	v_mfma_f32_16x16x32_bf16 v[6:9], v[176:179], v[218:221], v[6:9]
	v_mfma_f32_16x16x32_bf16 v[6:9], v[172:175], v[214:217], v[6:9]
	s_setprio 0
	s_barrier
	s_add_i32 s64, s64, 2
	s_add_u32 s34, s34, 0x100
	s_addc_u32 s35, s35, 0
	s_cmp_gt_u32 s64, 61
	s_cbranch_scc0 .LBB0_235
	s_and_b64 vcc, exec, s[20:21]
	s_cbranch_vccz .LBB0_238
	s_barrier

.LBB0_434:
	ds_read_b128 v[134:137], v204
	ds_read_b128 v[138:141], v204 offset:1024
	ds_read_b128 v[142:145], v204 offset:2048
	ds_read_b128 v[146:149], v204 offset:3072
	ds_read_b128 v[150:153], v205
	ds_read_b128 v[154:157], v205 offset:1024
	ds_read_b128 v[158:161], v205 offset:2048
	ds_read_b128 v[162:165], v205 offset:3072
	s_add_u32 s34, s22, s30
	s_addc_u32 s35, s23, s31
	s_add_u32 s38, s34, 0x100
	s_addc_u32 s39, s35, 0
	s_add_u32 s36, s60, s30
	s_addc_u32 s37, s61, s31
	s_add_u32 s34, s34, 0x180
	s_addc_u32 s35, s35, 0
	s_cmpk_eq_i32 s30, 0xb00
	s_cselect_b32 s35, s59, s35
	s_cselect_b32 s34, s58, s34
	s_cselect_b32 s37, s21, s37
	s_cselect_b32 s36, s20, s36
	s_cselect_b32 s39, s17, s39
	s_cselect_b32 s38, s16, s38
	v_lshl_add_u64 v[200:201], v[130:131], 0, s[30:31]
	s_add_i32 m0, s3, 0xc000
	ds_read_b128 v[166:169], v206
	ds_read_b128 v[170:173], v206 offset:1024
	ds_read_b128 v[174:177], v206 offset:2048
	ds_read_b128 v[178:181], v206 offset:3072
	ds_read_b128 v[182:185], v206 offset:4096
	ds_read_b128 v[208:211], v206 offset:5120
	ds_read_b128 v[214:217], v206 offset:6144
	ds_read_b128 v[218:221], v206 offset:7168
	global_load_lds_dwordx4 v[200:201], off
	v_lshl_add_u64 v[200:201], v[132:133], 0, s[30:31]
	s_add_i32 m0, s3, 0xe000
	s_nop 0
	global_load_lds_dwordx4 v[200:201], off
	s_waitcnt vmcnt(8)
	s_waitcnt lgkmcnt(0)
	s_barrier
	s_setprio 1
	s_waitcnt lgkmcnt(0)
	v_mfma_f32_16x16x32_bf16 v[126:129], v[134:137], v[166:169], v[126:129]
	v_mfma_f32_16x16x32_bf16 v[126:129], v[138:141], v[170:173], v[126:129]
	v_mfma_f32_16x16x32_bf16 v[122:125], v[146:149], v[170:173], v[122:125]
	v_mfma_f32_16x16x32_bf16 v[122:125], v[142:145], v[166:169], v[122:125]
	v_mfma_f32_16x16x32_bf16 v[106:109], v[142:145], v[174:177], v[106:109]
	v_mfma_f32_16x16x32_bf16 v[106:109], v[146:149], v[178:181], v[106:109]
	v_mfma_f32_16x16x32_bf16 v[110:113], v[138:141], v[178:181], v[110:113]
	v_mfma_f32_16x16x32_bf16 v[110:113], v[134:137], v[174:177], v[110:113]
	v_mfma_f32_16x16x32_bf16 v[94:97], v[134:137], v[182:185], v[94:97]
	v_mfma_f32_16x16x32_bf16 v[94:97], v[138:141], v[208:211], v[94:97]
	v_mfma_f32_16x16x32_bf16 v[90:93], v[146:149], v[208:211], v[90:93]
	v_mfma_f32_16x16x32_bf16 v[90:93], v[142:145], v[182:185], v[90:93]
	v_mfma_f32_16x16x32_bf16 v[74:77], v[142:145], v[214:217], v[74:77]
	v_mfma_f32_16x16x32_bf16 v[74:77], v[146:149], v[218:221], v[74:77]
	v_mfma_f32_16x16x32_bf16 v[78:81], v[138:141], v[218:221], v[78:81]
	v_mfma_f32_16x16x32_bf16 v[78:81], v[134:137], v[214:217], v[78:81]
	s_setprio 0
	s_setprio 1
	v_mfma_f32_16x16x32_bf16 v[118:121], v[150:153], v[166:169], v[118:121]
	v_mfma_f32_16x16x32_bf16 v[118:121], v[154:157], v[170:173], v[118:121]
	v_mfma_f32_16x16x32_bf16 v[114:117], v[162:165], v[170:173], v[114:117]
	v_mfma_f32_16x16x32_bf16 v[114:117], v[158:161], v[166:169], v[114:117]
	v_mfma_f32_16x16x32_bf16 v[98:101], v[158:161], v[174:177], v[98:101]
	v_mfma_f32_16x16x32_bf16 v[98:101], v[162:165], v[178:181], v[98:101]
	v_mfma_f32_16x16x32_bf16 v[102:105], v[154:157], v[178:181], v[102:105]
	v_mfma_f32_16x16x32_bf16 v[102:105], v[150:153], v[174:177], v[102:105]
	v_mfma_f32_16x16x32_bf16 v[86:89], v[150:153], v[182:185], v[86:89]
	v_mfma_f32_16x16x32_bf16 v[86:89], v[154:157], v[208:211], v[86:89]
	v_mfma_f32_16x16x32_bf16 v[82:85], v[162:165], v[208:211], v[82:85]
	v_mfma_f32_16x16x32_bf16 v[82:85], v[158:161], v[182:185], v[82:85]
	v_mfma_f32_16x16x32_bf16 v[66:69], v[158:161], v[214:217], v[66:69]
	v_mfma_f32_16x16x32_bf16 v[66:69], v[162:165], v[218:221], v[66:69]
	v_mfma_f32_16x16x32_bf16 v[70:73], v[154:157], v[218:221], v[70:73]
	v_mfma_f32_16x16x32_bf16 v[70:73], v[150:153], v[214:217], v[70:73]
	s_setprio 0
	s_barrier
	s_add_i32 s63, s52, s2
	v_lshl_add_u64 v[200:201], s[36:37], 0, v[188:189]
	s_mov_b32 m0, s63
	ds_read_b128 v[166:169], v206 offset:16384
	ds_read_b128 v[170:173], v206 offset:17408
	ds_read_b128 v[174:177], v206 offset:18432
	ds_read_b128 v[178:181], v206 offset:19456
	ds_read_b128 v[182:185], v206 offset:20480
	ds_read_b128 v[208:211], v206 offset:21504
	ds_read_b128 v[214:217], v206 offset:22528
	ds_read_b128 v[218:221], v206 offset:23552
	global_load_lds_dwordx4 v[200:201], off
	s_add_i32 m0, s63, 0x2000
	s_add_u32 s64, s36, 0x68000
	v_lshl_add_u64 v[222:223], s[36:37], 0, v[192:193]
	s_addc_u32 s65, s37, 0
	s_add_i32 s63, s53, s2
	global_load_lds_dwordx4 v[222:223], off
	v_lshl_add_u64 v[224:225], s[64:65], 0, v[188:189]
	s_mov_b32 m0, s63
	s_nop 0
	global_load_lds_dwordx4 v[224:225], off
	v_lshl_add_u64 v[224:225], s[64:65], 0, v[192:193]
	s_add_i32 m0, s63, 0x2000
	s_nop 0
	global_load_lds_dwordx4 v[224:225], off
	v_lshl_add_u64 v[224:225], s[38:39], 0, v[186:187]
	s_mov_b32 m0, s3
	s_nop 0
	global_load_lds_dwordx4 v[224:225], off
	v_lshl_add_u64 v[224:225], s[38:39], 0, v[190:191]
	s_mov_b32 m0, s33
	s_nop 0
	global_load_lds_dwordx4 v[224:225], off
	s_waitcnt vmcnt(8)
	s_waitcnt lgkmcnt(0)
	s_barrier
	s_setprio 1
	s_waitcnt lgkmcnt(0)
	v_mfma_f32_16x16x32_bf16 v[62:65], v[134:137], v[166:169], v[62:65]
	v_mfma_f32_16x16x32_bf16 v[62:65], v[138:141], v[170:173], v[62:65]
	v_mfma_f32_16x16x32_bf16 v[58:61], v[146:149], v[170:173], v[58:61]
	v_mfma_f32_16x16x32_bf16 v[58:61], v[142:145], v[166:169], v[58:61]
	v_mfma_f32_16x16x32_bf16 v[42:45], v[142:145], v[174:177], v[42:45]
	v_mfma_f32_16x16x32_bf16 v[42:45], v[146:149], v[178:181], v[42:45]
	v_mfma_f32_16x16x32_bf16 v[46:49], v[138:141], v[178:181], v[46:49]
	v_mfma_f32_16x16x32_bf16 v[46:49], v[134:137], v[174:177], v[46:49]
	v_mfma_f32_16x16x32_bf16 v[30:33], v[134:137], v[182:185], v[30:33]
	v_mfma_f32_16x16x32_bf16 v[30:33], v[138:141], v[208:211], v[30:33]
	v_mfma_f32_16x16x32_bf16 v[26:29], v[146:149], v[208:211], v[26:29]
	v_mfma_f32_16x16x32_bf16 v[26:29], v[142:145], v[182:185], v[26:29]
	v_mfma_f32_16x16x32_bf16 v[10:13], v[142:145], v[214:217], v[10:13]
	v_mfma_f32_16x16x32_bf16 v[10:13], v[146:149], v[218:221], v[10:13]
	v_mfma_f32_16x16x32_bf16 v[14:17], v[138:141], v[218:221], v[14:17]
	v_mfma_f32_16x16x32_bf16 v[14:17], v[134:137], v[214:217], v[14:17]
	s_setprio 0
	s_setprio 1
	v_mfma_f32_16x16x32_bf16 v[54:57], v[150:153], v[166:169], v[54:57]
	v_mfma_f32_16x16x32_bf16 v[54:57], v[154:157], v[170:173], v[54:57]
	v_mfma_f32_16x16x32_bf16 v[50:53], v[162:165], v[170:173], v[50:53]
	v_mfma_f32_16x16x32_bf16 v[50:53], v[158:161], v[166:169], v[50:53]
	v_mfma_f32_16x16x32_bf16 v[34:37], v[158:161], v[174:177], v[34:37]
	v_mfma_f32_16x16x32_bf16 v[34:37], v[162:165], v[178:181], v[34:37]
	v_mfma_f32_16x16x32_bf16 v[38:41], v[154:157], v[178:181], v[38:41]
	v_mfma_f32_16x16x32_bf16 v[38:41], v[150:153], v[174:177], v[38:41]
	v_mfma_f32_16x16x32_bf16 v[22:25], v[150:153], v[182:185], v[22:25]
	v_mfma_f32_16x16x32_bf16 v[22:25], v[154:157], v[208:211], v[22:25]
	v_mfma_f32_16x16x32_bf16 v[18:21], v[162:165], v[208:211], v[18:21]
	v_mfma_f32_16x16x32_bf16 v[18:21], v[158:161], v[182:185], v[18:21]
	v_mfma_f32_16x16x32_bf16 v[2:5], v[158:161], v[214:217], v[2:5]
	v_mfma_f32_16x16x32_bf16 v[2:5], v[162:165], v[218:221], v[2:5]
	v_mfma_f32_16x16x32_bf16 v[6:9], v[154:157], v[218:221], v[6:9]
	v_mfma_f32_16x16x32_bf16 v[6:9], v[150:153], v[214:217], v[6:9]
	s_setprio 0
	s_barrier
	s_add_i32 s63, 0, 0x18000
	s_add_i32 s64, 0, 0x1c000
	v_add_u32_e32 v146, s63, v202
	v_add_u32_e32 v162, s64, v202
	ds_read_b128 v[134:137], v146
	ds_read_b128 v[138:141], v146 offset:1024
	ds_read_b128 v[142:145], v146 offset:2048
	ds_read_b128 v[146:149], v146 offset:3072
	ds_read_b128 v[150:153], v162
	ds_read_b128 v[154:157], v162 offset:1024
	ds_read_b128 v[158:161], v162 offset:2048
	ds_read_b128 v[162:165], v162 offset:3072
	s_add_u32 s38, s38, 0x188000
	s_addc_u32 s39, s39, 0
	s_mov_b32 m0, s40
	v_lshl_add_u64 v[224:225], s[38:39], 0, v[186:187]
	ds_read_b128 v[166:169], v206 offset:32768
	ds_read_b128 v[170:173], v206 offset:33792
	ds_read_b128 v[174:177], v206 offset:34816
	ds_read_b128 v[178:181], v206 offset:35840
	ds_read_b128 v[182:185], v206 offset:36864
	ds_read_b128 v[208:211], v206 offset:37888
	ds_read_b128 v[214:217], v206 offset:38912
	ds_read_b128 v[218:221], v206 offset:39936
	global_load_lds_dwordx4 v[224:225], off
	v_lshl_add_u64 v[224:225], s[38:39], 0, v[190:191]
	s_mov_b32 m0, s41
	s_nop 0
	global_load_lds_dwordx4 v[224:225], off
	s_waitcnt vmcnt(8)
	s_waitcnt lgkmcnt(0)
	s_barrier
	s_setprio 1
	s_waitcnt lgkmcnt(0)
	v_mfma_f32_16x16x32_bf16 v[126:129], v[134:137], v[166:169], v[126:129]
	v_mfma_f32_16x16x32_bf16 v[126:129], v[138:141], v[170:173], v[126:129]
	v_mfma_f32_16x16x32_bf16 v[122:125], v[146:149], v[170:173], v[122:125]
	v_mfma_f32_16x16x32_bf16 v[122:125], v[142:145], v[166:169], v[122:125]
	v_mfma_f32_16x16x32_bf16 v[106:109], v[142:145], v[174:177], v[106:109]
	v_mfma_f32_16x16x32_bf16 v[106:109], v[146:149], v[178:181], v[106:109]
	v_mfma_f32_16x16x32_bf16 v[110:113], v[138:141], v[178:181], v[110:113]
	v_mfma_f32_16x16x32_bf16 v[110:113], v[134:137], v[174:177], v[110:113]
	v_mfma_f32_16x16x32_bf16 v[94:97], v[134:137], v[182:185], v[94:97]
	v_mfma_f32_16x16x32_bf16 v[94:97], v[138:141], v[208:211], v[94:97]
	v_mfma_f32_16x16x32_bf16 v[90:93], v[146:149], v[208:211], v[90:93]
	v_mfma_f32_16x16x32_bf16 v[90:93], v[142:145], v[182:185], v[90:93]
	v_mfma_f32_16x16x32_bf16 v[74:77], v[142:145], v[214:217], v[74:77]
	v_mfma_f32_16x16x32_bf16 v[74:77], v[146:149], v[218:221], v[74:77]
	v_mfma_f32_16x16x32_bf16 v[78:81], v[138:141], v[218:221], v[78:81]
	v_mfma_f32_16x16x32_bf16 v[78:81], v[134:137], v[214:217], v[78:81]
	s_setprio 0
	s_setprio 1
	v_mfma_f32_16x16x32_bf16 v[118:121], v[150:153], v[166:169], v[118:121]
	v_mfma_f32_16x16x32_bf16 v[118:121], v[154:157], v[170:173], v[118:121]
	v_mfma_f32_16x16x32_bf16 v[114:117], v[162:165], v[170:173], v[114:117]
	v_mfma_f32_16x16x32_bf16 v[114:117], v[158:161], v[166:169], v[114:117]
	v_mfma_f32_16x16x32_bf16 v[98:101], v[158:161], v[174:177], v[98:101]
	v_mfma_f32_16x16x32_bf16 v[98:101], v[162:165], v[178:181], v[98:101]
	v_mfma_f32_16x16x32_bf16 v[102:105], v[154:157], v[178:181], v[102:105]
	v_mfma_f32_16x16x32_bf16 v[102:105], v[150:153], v[174:177], v[102:105]
	v_mfma_f32_16x16x32_bf16 v[86:89], v[150:153], v[182:185], v[86:89]
	v_mfma_f32_16x16x32_bf16 v[86:89], v[154:157], v[208:211], v[86:89]
	v_mfma_f32_16x16x32_bf16 v[82:85], v[162:165], v[208:211], v[82:85]
	v_mfma_f32_16x16x32_bf16 v[82:85], v[158:161], v[182:185], v[82:85]
	v_mfma_f32_16x16x32_bf16 v[66:69], v[158:161], v[214:217], v[66:69]
	v_mfma_f32_16x16x32_bf16 v[66:69], v[162:165], v[218:221], v[66:69]
	v_mfma_f32_16x16x32_bf16 v[70:73], v[154:157], v[218:221], v[70:73]
	v_mfma_f32_16x16x32_bf16 v[70:73], v[150:153], v[214:217], v[70:73]
	s_setprio 0
	s_barrier
	s_add_i32 s38, s63, s2
	v_lshl_add_u64 v[200:201], v[200:201], 0, s[12:13]
	s_mov_b32 m0, s38
	ds_read_b128 v[166:169], v206 offset:49152
	ds_read_b128 v[170:173], v206 offset:50176
	ds_read_b128 v[174:177], v206 offset:51200
	ds_read_b128 v[178:181], v206 offset:52224
	ds_read_b128 v[182:185], v206 offset:53248
	ds_read_b128 v[208:211], v206 offset:54272
	ds_read_b128 v[214:217], v206 offset:55296
	ds_read_b128 v[218:221], v206 offset:56320
	global_load_lds_dwordx4 v[200:201], off
	s_add_i32 m0, s38, 0x2000
	s_add_u32 s36, s36, 0x68080
	v_lshl_add_u64 v[200:201], v[222:223], 0, s[12:13]
	s_addc_u32 s37, s37, 0
	s_add_i32 s38, s64, s2
	global_load_lds_dwordx4 v[200:201], off
	v_lshl_add_u64 v[200:201], s[36:37], 0, v[188:189]
	s_mov_b32 m0, s38
	s_nop 0
	global_load_lds_dwordx4 v[200:201], off
	v_lshl_add_u64 v[200:201], s[36:37], 0, v[192:193]
	s_add_i32 m0, s38, 0x2000
	s_nop 0
	global_load_lds_dwordx4 v[200:201], off
	v_lshl_add_u64 v[200:201], s[34:35], 0, v[186:187]
	s_mov_b32 m0, s50
	s_nop 0
	global_load_lds_dwordx4 v[200:201], off
	v_lshl_add_u64 v[200:201], s[34:35], 0, v[190:191]
	s_mov_b32 m0, s51
	s_nop 0
	global_load_lds_dwordx4 v[200:201], off
	s_waitcnt vmcnt(8)
	s_waitcnt lgkmcnt(0)
	s_barrier
	s_setprio 1
	s_waitcnt lgkmcnt(0)
	v_mfma_f32_16x16x32_bf16 v[62:65], v[134:137], v[166:169], v[62:65]
	v_mfma_f32_16x16x32_bf16 v[62:65], v[138:141], v[170:173], v[62:65]
	v_mfma_f32_16x16x32_bf16 v[58:61], v[146:149], v[170:173], v[58:61]
	v_mfma_f32_16x16x32_bf16 v[58:61], v[142:145], v[166:169], v[58:61]
	v_mfma_f32_16x16x32_bf16 v[42:45], v[142:145], v[174:177], v[42:45]
	v_mfma_f32_16x16x32_bf16 v[42:45], v[146:149], v[178:181], v[42:45]
	v_mfma_f32_16x16x32_bf16 v[46:49], v[138:141], v[178:181], v[46:49]
	v_mfma_f32_16x16x32_bf16 v[46:49], v[134:137], v[174:177], v[46:49]
	v_mfma_f32_16x16x32_bf16 v[30:33], v[134:137], v[182:185], v[30:33]
	v_mfma_f32_16x16x32_bf16 v[30:33], v[138:141], v[208:211], v[30:33]
	v_mfma_f32_16x16x32_bf16 v[26:29], v[146:149], v[208:211], v[26:29]
	v_mfma_f32_16x16x32_bf16 v[26:29], v[142:145], v[182:185], v[26:29]
	v_mfma_f32_16x16x32_bf16 v[10:13], v[142:145], v[214:217], v[10:13]
	v_mfma_f32_16x16x32_bf16 v[10:13], v[146:149], v[218:221], v[10:13]
	v_mfma_f32_16x16x32_bf16 v[14:17], v[138:141], v[218:221], v[14:17]
	v_mfma_f32_16x16x32_bf16 v[14:17], v[134:137], v[214:217], v[14:17]
	s_setprio 0
	s_setprio 1
	v_mfma_f32_16x16x32_bf16 v[54:57], v[150:153], v[166:169], v[54:57]
	v_mfma_f32_16x16x32_bf16 v[54:57], v[154:157], v[170:173], v[54:57]
	v_mfma_f32_16x16x32_bf16 v[50:53], v[162:165], v[170:173], v[50:53]
	v_mfma_f32_16x16x32_bf16 v[50:53], v[158:161], v[166:169], v[50:53]
	v_mfma_f32_16x16x32_bf16 v[34:37], v[158:161], v[174:177], v[34:37]
	v_mfma_f32_16x16x32_bf16 v[34:37], v[162:165], v[178:181], v[34:37]
	v_mfma_f32_16x16x32_bf16 v[38:41], v[154:157], v[178:181], v[38:41]
	v_mfma_f32_16x16x32_bf16 v[38:41], v[150:153], v[174:177], v[38:41]
	v_mfma_f32_16x16x32_bf16 v[22:25], v[150:153], v[182:185], v[22:25]
	v_mfma_f32_16x16x32_bf16 v[22:25], v[154:157], v[208:211], v[22:25]
	v_mfma_f32_16x16x32_bf16 v[18:21], v[162:165], v[208:211], v[18:21]
	v_mfma_f32_16x16x32_bf16 v[18:21], v[158:161], v[182:185], v[18:21]
	v_mfma_f32_16x16x32_bf16 v[2:5], v[158:161], v[214:217], v[2:5]
	v_mfma_f32_16x16x32_bf16 v[2:5], v[162:165], v[218:221], v[2:5]
	v_mfma_f32_16x16x32_bf16 v[6:9], v[154:157], v[218:221], v[6:9]
	v_mfma_f32_16x16x32_bf16 v[6:9], v[150:153], v[214:217], v[6:9]
	s_setprio 0
	s_barrier
	s_add_i32 s62, s62, 2
	s_add_u32 s30, s30, 0x100
	s_addc_u32 s31, s31, 0
	s_cmp_gt_u32 s62, 21
	s_cbranch_scc0 .LBB0_434
	s_and_b64 vcc, exec, s[14:15]
	s_cbranch_vccz .LBB0_437
	s_barrier

.LBB0_519:
	s_add_i32 s39, s56, 0xfffe8000
	s_and_b32 s38, s36, 0x100
	s_and_b32 s39, s39, 0x3e0000
	s_or_b32 s38, s38, s39
	s_add_u32 s57, s34, s38
	s_addc_u32 s59, s35, 0
	s_add_u32 s38, s36, 0x100
	s_addc_u32 s39, s37, 0
	s_add_i32 s41, s56, 0xffff8000
	s_and_b32 s40, s38, 0x100
	s_and_b32 s41, s41, 0x7e0000
	s_or_b32 s40, s41, s40
	s_add_u32 s40, s34, s40
	s_addc_u32 s41, s35, 0
	s_add_u32 s58, s53, s36
	s_addc_u32 s37, s54, s37
	s_add_i32 s42, s36, 0x180
	s_and_b32 s42, s42, 0x180
	s_and_b32 s43, s56, 0x7e0000
	s_or_b32 s42, s43, s42
	s_add_u32 s60, s34, s42
	s_addc_u32 s61, s35, 0
	s_cmpk_eq_i32 s36, 0x3f00
	s_cselect_b32 s43, s1, s41
	s_cselect_b32 s42, s21, s40
	s_cselect_b32 s41, s23, s37
	s_cselect_b32 s40, s22, s58
	s_cselect_b32 s37, s52, s61
	s_cselect_b32 s36, s31, s60
	s_add_i32 s60, 0, 0x10000
	v_add_u32_e32 v1, s60, v199
	ds_read_b128 v[130:133], v1
	ds_read_b128 v[134:137], v1 offset:1024
	ds_read_b128 v[138:141], v1 offset:2048
	ds_read_b128 v[142:145], v1 offset:3072
	ds_read_b128 v[146:149], v201
	ds_read_b128 v[150:153], v201 offset:1024
	ds_read_b128 v[154:157], v201 offset:2048
	ds_read_b128 v[158:161], v201 offset:3072
	s_add_u32 s58, s57, 0x10080
	s_addc_u32 s59, s59, 0
	v_lshl_add_u64 v[208:209], s[58:59], 0, v[178:179]
	s_add_i32 m0, s3, 0xc000
	ds_read_b128 v[162:165], v202
	ds_read_b128 v[166:169], v202 offset:1024
	ds_read_b128 v[170:173], v202 offset:2048
	ds_read_b128 v[174:177], v202 offset:3072
	ds_read_b128 v[186:189], v202 offset:4096
	ds_read_b128 v[190:193], v202 offset:5120
	ds_read_b128 v[194:197], v202 offset:6144
	ds_read_b128 v[204:207], v202 offset:7168
	global_load_lds_dwordx4 v[208:209], off
	v_lshl_add_u64 v[208:209], s[58:59], 0, v[182:183]
	s_add_i32 m0, s3, 0xe000
	s_nop 0
	global_load_lds_dwordx4 v[208:209], off
	s_waitcnt vmcnt(8)
	s_waitcnt lgkmcnt(0)
	s_barrier
	s_setprio 1
	s_waitcnt lgkmcnt(0)
	v_mfma_f32_16x16x32_bf16 v[126:129], v[130:133], v[162:165], v[126:129]
	v_mfma_f32_16x16x32_bf16 v[126:129], v[134:137], v[166:169], v[126:129]
	v_mfma_f32_16x16x32_bf16 v[122:125], v[142:145], v[166:169], v[122:125]
	v_mfma_f32_16x16x32_bf16 v[122:125], v[138:141], v[162:165], v[122:125]
	v_mfma_f32_16x16x32_bf16 v[106:109], v[138:141], v[170:173], v[106:109]
	v_mfma_f32_16x16x32_bf16 v[106:109], v[142:145], v[174:177], v[106:109]
	v_mfma_f32_16x16x32_bf16 v[110:113], v[134:137], v[174:177], v[110:113]
	v_mfma_f32_16x16x32_bf16 v[110:113], v[130:133], v[170:173], v[110:113]
	v_mfma_f32_16x16x32_bf16 v[94:97], v[130:133], v[186:189], v[94:97]
	v_mfma_f32_16x16x32_bf16 v[94:97], v[134:137], v[190:193], v[94:97]
	v_mfma_f32_16x16x32_bf16 v[90:93], v[142:145], v[190:193], v[90:93]
	v_mfma_f32_16x16x32_bf16 v[90:93], v[138:141], v[186:189], v[90:93]
	v_mfma_f32_16x16x32_bf16 v[74:77], v[138:141], v[194:197], v[74:77]
	v_mfma_f32_16x16x32_bf16 v[74:77], v[142:145], v[204:207], v[74:77]
	v_mfma_f32_16x16x32_bf16 v[78:81], v[134:137], v[204:207], v[78:81]
	v_mfma_f32_16x16x32_bf16 v[78:81], v[130:133], v[194:197], v[78:81]
	s_setprio 0
	s_setprio 1
	v_mfma_f32_16x16x32_bf16 v[118:121], v[146:149], v[162:165], v[118:121]
	v_mfma_f32_16x16x32_bf16 v[118:121], v[150:153], v[166:169], v[118:121]
	v_mfma_f32_16x16x32_bf16 v[114:117], v[158:161], v[166:169], v[114:117]
	v_mfma_f32_16x16x32_bf16 v[114:117], v[154:157], v[162:165], v[114:117]
	v_mfma_f32_16x16x32_bf16 v[98:101], v[154:157], v[170:173], v[98:101]
	v_mfma_f32_16x16x32_bf16 v[98:101], v[158:161], v[174:177], v[98:101]
	v_mfma_f32_16x16x32_bf16 v[102:105], v[150:153], v[174:177], v[102:105]
	v_mfma_f32_16x16x32_bf16 v[102:105], v[146:149], v[170:173], v[102:105]
	v_mfma_f32_16x16x32_bf16 v[86:89], v[146:149], v[186:189], v[86:89]
	v_mfma_f32_16x16x32_bf16 v[86:89], v[150:153], v[190:193], v[86:89]
	v_mfma_f32_16x16x32_bf16 v[82:85], v[158:161], v[190:193], v[82:85]
	v_mfma_f32_16x16x32_bf16 v[82:85], v[154:157], v[186:189], v[82:85]
	v_mfma_f32_16x16x32_bf16 v[66:69], v[154:157], v[194:197], v[66:69]
	v_mfma_f32_16x16x32_bf16 v[66:69], v[158:161], v[204:207], v[66:69]
	v_mfma_f32_16x16x32_bf16 v[70:73], v[150:153], v[204:207], v[70:73]
	v_mfma_f32_16x16x32_bf16 v[70:73], v[146:149], v[194:197], v[70:73]
	s_setprio 0
	s_barrier
	s_add_i32 s57, s60, s2
	v_lshl_add_u64 v[208:209], s[40:41], 0, v[180:181]
	s_mov_b32 m0, s57
	ds_read_b128 v[162:165], v202 offset:16384
	ds_read_b128 v[166:169], v202 offset:17408
	ds_read_b128 v[170:173], v202 offset:18432
	ds_read_b128 v[174:177], v202 offset:19456
	ds_read_b128 v[186:189], v202 offset:20480
	ds_read_b128 v[190:193], v202 offset:21504
	ds_read_b128 v[194:197], v202 offset:22528
	ds_read_b128 v[204:207], v202 offset:23552
	global_load_lds_dwordx4 v[208:209], off
	s_add_i32 m0, s57, 0x2000
	s_add_u32 s58, s40, 0x208000
	v_lshl_add_u64 v[210:211], s[40:41], 0, v[184:185]
	s_addc_u32 s59, s41, 0
	s_add_i32 s57, s49, s2
	global_load_lds_dwordx4 v[210:211], off
	v_lshl_add_u64 v[214:215], s[58:59], 0, v[180:181]
	s_mov_b32 m0, s57
	s_nop 0
	global_load_lds_dwordx4 v[214:215], off
	v_lshl_add_u64 v[214:215], s[58:59], 0, v[184:185]
	s_add_i32 m0, s57, 0x2000
	s_nop 0
	global_load_lds_dwordx4 v[214:215], off
	v_lshl_add_u64 v[214:215], s[42:43], 0, v[178:179]
	s_mov_b32 m0, s3
	s_nop 0
	global_load_lds_dwordx4 v[214:215], off
	v_lshl_add_u64 v[214:215], s[42:43], 0, v[182:183]
	s_mov_b32 m0, s33
	s_nop 0
	global_load_lds_dwordx4 v[214:215], off
	s_waitcnt vmcnt(8)
	s_waitcnt lgkmcnt(0)
	s_barrier
	s_setprio 1
	s_waitcnt lgkmcnt(0)
	v_mfma_f32_16x16x32_bf16 v[62:65], v[130:133], v[162:165], v[62:65]
	v_mfma_f32_16x16x32_bf16 v[62:65], v[134:137], v[166:169], v[62:65]
	v_mfma_f32_16x16x32_bf16 v[58:61], v[142:145], v[166:169], v[58:61]
	v_mfma_f32_16x16x32_bf16 v[58:61], v[138:141], v[162:165], v[58:61]
	v_mfma_f32_16x16x32_bf16 v[42:45], v[138:141], v[170:173], v[42:45]
	v_mfma_f32_16x16x32_bf16 v[42:45], v[142:145], v[174:177], v[42:45]
	v_mfma_f32_16x16x32_bf16 v[46:49], v[134:137], v[174:177], v[46:49]
	v_mfma_f32_16x16x32_bf16 v[46:49], v[130:133], v[170:173], v[46:49]
	v_mfma_f32_16x16x32_bf16 v[30:33], v[130:133], v[186:189], v[30:33]
	v_mfma_f32_16x16x32_bf16 v[30:33], v[134:137], v[190:193], v[30:33]
	v_mfma_f32_16x16x32_bf16 v[26:29], v[142:145], v[190:193], v[26:29]
	v_mfma_f32_16x16x32_bf16 v[26:29], v[138:141], v[186:189], v[26:29]
	v_mfma_f32_16x16x32_bf16 v[10:13], v[138:141], v[194:197], v[10:13]
	v_mfma_f32_16x16x32_bf16 v[10:13], v[142:145], v[204:207], v[10:13]
	v_mfma_f32_16x16x32_bf16 v[14:17], v[134:137], v[204:207], v[14:17]
	v_mfma_f32_16x16x32_bf16 v[14:17], v[130:133], v[194:197], v[14:17]
	s_setprio 0
	s_setprio 1
	v_mfma_f32_16x16x32_bf16 v[54:57], v[146:149], v[162:165], v[54:57]
	v_mfma_f32_16x16x32_bf16 v[54:57], v[150:153], v[166:169], v[54:57]
	v_mfma_f32_16x16x32_bf16 v[50:53], v[158:161], v[166:169], v[50:53]
	v_mfma_f32_16x16x32_bf16 v[50:53], v[154:157], v[162:165], v[50:53]
	v_mfma_f32_16x16x32_bf16 v[34:37], v[154:157], v[170:173], v[34:37]
	v_mfma_f32_16x16x32_bf16 v[34:37], v[158:161], v[174:177], v[34:37]
	v_mfma_f32_16x16x32_bf16 v[38:41], v[150:153], v[174:177], v[38:41]
	v_mfma_f32_16x16x32_bf16 v[38:41], v[146:149], v[170:173], v[38:41]
	v_mfma_f32_16x16x32_bf16 v[22:25], v[146:149], v[186:189], v[22:25]
	v_mfma_f32_16x16x32_bf16 v[22:25], v[150:153], v[190:193], v[22:25]
	v_mfma_f32_16x16x32_bf16 v[18:21], v[158:161], v[190:193], v[18:21]
	v_mfma_f32_16x16x32_bf16 v[18:21], v[154:157], v[186:189], v[18:21]
	v_mfma_f32_16x16x32_bf16 v[2:5], v[154:157], v[194:197], v[2:5]
	v_mfma_f32_16x16x32_bf16 v[2:5], v[158:161], v[204:207], v[2:5]
	v_mfma_f32_16x16x32_bf16 v[6:9], v[150:153], v[204:207], v[6:9]
	v_mfma_f32_16x16x32_bf16 v[6:9], v[146:149], v[194:197], v[6:9]
	s_setprio 0
	s_barrier
	s_add_i32 s57, 0, 0x18000
	v_add_u32_e32 v1, s57, v199
	s_add_i32 s58, 0, 0x1c000
	ds_read_b128 v[130:133], v1
	ds_read_b128 v[134:137], v1 offset:1024
	ds_read_b128 v[138:141], v1 offset:2048
	ds_read_b128 v[142:145], v1 offset:3072
	v_add_u32_e32 v1, s58, v199
	ds_read_b128 v[146:149], v1
	ds_read_b128 v[150:153], v1 offset:1024
	ds_read_b128 v[154:157], v1 offset:2048
	ds_read_b128 v[158:161], v1 offset:3072
	s_add_u32 s42, s42, 0x10000
	s_addc_u32 s43, s43, 0
	s_mov_b32 m0, s44
	v_lshl_add_u64 v[214:215], s[42:43], 0, v[178:179]
	ds_read_b128 v[162:165], v202 offset:32768
	ds_read_b128 v[166:169], v202 offset:33792
	ds_read_b128 v[170:173], v202 offset:34816
	ds_read_b128 v[174:177], v202 offset:35840
	ds_read_b128 v[186:189], v202 offset:36864
	ds_read_b128 v[190:193], v202 offset:37888
	ds_read_b128 v[194:197], v202 offset:38912
	ds_read_b128 v[204:207], v202 offset:39936
	global_load_lds_dwordx4 v[214:215], off
	v_lshl_add_u64 v[214:215], s[42:43], 0, v[182:183]
	s_mov_b32 m0, s45
	s_nop 0
	global_load_lds_dwordx4 v[214:215], off
	s_waitcnt vmcnt(8)
	s_waitcnt lgkmcnt(0)
	s_barrier
	s_setprio 1
	s_waitcnt lgkmcnt(0)
	v_mfma_f32_16x16x32_bf16 v[126:129], v[130:133], v[162:165], v[126:129]
	v_mfma_f32_16x16x32_bf16 v[126:129], v[134:137], v[166:169], v[126:129]
	v_mfma_f32_16x16x32_bf16 v[122:125], v[142:145], v[166:169], v[122:125]
	v_mfma_f32_16x16x32_bf16 v[122:125], v[138:141], v[162:165], v[122:125]
	v_mfma_f32_16x16x32_bf16 v[106:109], v[138:141], v[170:173], v[106:109]
	v_mfma_f32_16x16x32_bf16 v[106:109], v[142:145], v[174:177], v[106:109]
	v_mfma_f32_16x16x32_bf16 v[110:113], v[134:137], v[174:177], v[110:113]
	v_mfma_f32_16x16x32_bf16 v[110:113], v[130:133], v[170:173], v[110:113]
	v_mfma_f32_16x16x32_bf16 v[94:97], v[130:133], v[186:189], v[94:97]
	v_mfma_f32_16x16x32_bf16 v[94:97], v[134:137], v[190:193], v[94:97]
	v_mfma_f32_16x16x32_bf16 v[90:93], v[142:145], v[190:193], v[90:93]
	v_mfma_f32_16x16x32_bf16 v[90:93], v[138:141], v[186:189], v[90:93]
	v_mfma_f32_16x16x32_bf16 v[74:77], v[138:141], v[194:197], v[74:77]
	v_mfma_f32_16x16x32_bf16 v[74:77], v[142:145], v[204:207], v[74:77]
	v_mfma_f32_16x16x32_bf16 v[78:81], v[134:137], v[204:207], v[78:81]
	v_mfma_f32_16x16x32_bf16 v[78:81], v[130:133], v[194:197], v[78:81]
	s_setprio 0
	s_setprio 1
	v_mfma_f32_16x16x32_bf16 v[118:121], v[146:149], v[162:165], v[118:121]
	v_mfma_f32_16x16x32_bf16 v[118:121], v[150:153], v[166:169], v[118:121]
	v_mfma_f32_16x16x32_bf16 v[114:117], v[158:161], v[166:169], v[114:117]
	v_mfma_f32_16x16x32_bf16 v[114:117], v[154:157], v[162:165], v[114:117]
	v_mfma_f32_16x16x32_bf16 v[98:101], v[154:157], v[170:173], v[98:101]
	v_mfma_f32_16x16x32_bf16 v[98:101], v[158:161], v[174:177], v[98:101]
	v_mfma_f32_16x16x32_bf16 v[102:105], v[150:153], v[174:177], v[102:105]
	v_mfma_f32_16x16x32_bf16 v[102:105], v[146:149], v[170:173], v[102:105]
	v_mfma_f32_16x16x32_bf16 v[86:89], v[146:149], v[186:189], v[86:89]
	v_mfma_f32_16x16x32_bf16 v[86:89], v[150:153], v[190:193], v[86:89]
	v_mfma_f32_16x16x32_bf16 v[82:85], v[158:161], v[190:193], v[82:85]
	v_mfma_f32_16x16x32_bf16 v[82:85], v[154:157], v[186:189], v[82:85]
	v_mfma_f32_16x16x32_bf16 v[66:69], v[154:157], v[194:197], v[66:69]
	v_mfma_f32_16x16x32_bf16 v[66:69], v[158:161], v[204:207], v[66:69]
	v_mfma_f32_16x16x32_bf16 v[70:73], v[150:153], v[204:207], v[70:73]
	v_mfma_f32_16x16x32_bf16 v[70:73], v[146:149], v[194:197], v[70:73]
	s_setprio 0
	s_barrier
	s_add_i32 s42, s57, s2
	v_lshl_add_u64 v[208:209], v[208:209], 0, s[16:17]
	s_mov_b32 m0, s42
	ds_read_b128 v[162:165], v202 offset:49152
	ds_read_b128 v[166:169], v202 offset:50176
	ds_read_b128 v[170:173], v202 offset:51200
	ds_read_b128 v[174:177], v202 offset:52224
	ds_read_b128 v[186:189], v202 offset:53248
	ds_read_b128 v[190:193], v202 offset:54272
	ds_read_b128 v[194:197], v202 offset:55296
	ds_read_b128 v[204:207], v202 offset:56320
	global_load_lds_dwordx4 v[208:209], off
	s_add_i32 m0, s42, 0x2000
	s_add_u32 s40, s40, 0x208080
	v_lshl_add_u64 v[208:209], v[210:211], 0, s[16:17]
	s_addc_u32 s41, s41, 0
	s_add_i32 s42, s58, s2
	global_load_lds_dwordx4 v[208:209], off
	v_lshl_add_u64 v[208:209], s[40:41], 0, v[180:181]
	s_mov_b32 m0, s42
	s_nop 0
	global_load_lds_dwordx4 v[208:209], off
	v_lshl_add_u64 v[208:209], s[40:41], 0, v[184:185]
	s_add_i32 m0, s42, 0x2000
	s_nop 0
	global_load_lds_dwordx4 v[208:209], off
	v_lshl_add_u64 v[208:209], s[36:37], 0, v[178:179]
	s_mov_b32 m0, s47
	s_nop 0
	global_load_lds_dwordx4 v[208:209], off
	v_lshl_add_u64 v[208:209], s[36:37], 0, v[182:183]
	s_mov_b32 m0, s48
	s_nop 0
	global_load_lds_dwordx4 v[208:209], off
	s_waitcnt vmcnt(8)
	s_waitcnt lgkmcnt(0)
	s_barrier
	s_setprio 1
	s_waitcnt lgkmcnt(0)
	v_mfma_f32_16x16x32_bf16 v[62:65], v[130:133], v[162:165], v[62:65]
	v_mfma_f32_16x16x32_bf16 v[62:65], v[134:137], v[166:169], v[62:65]
	v_mfma_f32_16x16x32_bf16 v[58:61], v[142:145], v[166:169], v[58:61]
	v_mfma_f32_16x16x32_bf16 v[58:61], v[138:141], v[162:165], v[58:61]
	v_mfma_f32_16x16x32_bf16 v[42:45], v[138:141], v[170:173], v[42:45]
	v_mfma_f32_16x16x32_bf16 v[42:45], v[142:145], v[174:177], v[42:45]
	v_mfma_f32_16x16x32_bf16 v[46:49], v[134:137], v[174:177], v[46:49]
	v_mfma_f32_16x16x32_bf16 v[46:49], v[130:133], v[170:173], v[46:49]
	v_mfma_f32_16x16x32_bf16 v[30:33], v[130:133], v[186:189], v[30:33]
	v_mfma_f32_16x16x32_bf16 v[30:33], v[134:137], v[190:193], v[30:33]
	v_mfma_f32_16x16x32_bf16 v[26:29], v[142:145], v[190:193], v[26:29]
	v_mfma_f32_16x16x32_bf16 v[26:29], v[138:141], v[186:189], v[26:29]
	v_mfma_f32_16x16x32_bf16 v[10:13], v[138:141], v[194:197], v[10:13]
	v_mfma_f32_16x16x32_bf16 v[10:13], v[142:145], v[204:207], v[10:13]
	v_mfma_f32_16x16x32_bf16 v[14:17], v[134:137], v[204:207], v[14:17]
	v_mfma_f32_16x16x32_bf16 v[14:17], v[130:133], v[194:197], v[14:17]
	s_setprio 0
	s_setprio 1
	v_mfma_f32_16x16x32_bf16 v[54:57], v[146:149], v[162:165], v[54:57]
	v_mfma_f32_16x16x32_bf16 v[54:57], v[150:153], v[166:169], v[54:57]
	v_mfma_f32_16x16x32_bf16 v[50:53], v[158:161], v[166:169], v[50:53]
	v_mfma_f32_16x16x32_bf16 v[50:53], v[154:157], v[162:165], v[50:53]
	v_mfma_f32_16x16x32_bf16 v[34:37], v[154:157], v[170:173], v[34:37]
	v_mfma_f32_16x16x32_bf16 v[34:37], v[158:161], v[174:177], v[34:37]
	v_mfma_f32_16x16x32_bf16 v[38:41], v[150:153], v[174:177], v[38:41]
	v_mfma_f32_16x16x32_bf16 v[38:41], v[146:149], v[170:173], v[38:41]
	v_mfma_f32_16x16x32_bf16 v[22:25], v[146:149], v[186:189], v[22:25]
	v_mfma_f32_16x16x32_bf16 v[22:25], v[150:153], v[190:193], v[22:25]
	v_mfma_f32_16x16x32_bf16 v[18:21], v[158:161], v[190:193], v[18:21]
	v_mfma_f32_16x16x32_bf16 v[18:21], v[154:157], v[186:189], v[18:21]
	v_mfma_f32_16x16x32_bf16 v[2:5], v[154:157], v[194:197], v[2:5]
	v_mfma_f32_16x16x32_bf16 v[2:5], v[158:161], v[204:207], v[2:5]
	v_mfma_f32_16x16x32_bf16 v[6:9], v[150:153], v[204:207], v[6:9]
	v_mfma_f32_16x16x32_bf16 v[6:9], v[146:149], v[194:197], v[6:9]
	s_setprio 0
	s_barrier
	s_add_i32 s55, s55, 2
	s_add_i32 s56, s56, 0x10000
	s_cmpk_gt_u32 s55, 0x7d
	s_mov_b64 s[36:37], s[38:39]
	s_cbranch_scc0 .LBB0_519
	s_and_b64 vcc, exec, s[18:19]
	s_cbranch_vccz .LBB0_522
	s_barrier

.LBB0_612:
	ds_read_b128 v[166:169], v152
	ds_read_b128 v[170:173], v152 offset:1024
	ds_read_b128 v[174:177], v152 offset:2048
	ds_read_b128 v[178:181], v152 offset:3072
	ds_read_b128 v[182:185], v153
	ds_read_b128 v[186:189], v153 offset:1024
	ds_read_b128 v[190:193], v153 offset:2048
	ds_read_b128 v[194:197], v153 offset:3072
	s_add_u32 s26, s4, s22
	s_addc_u32 s27, s5, s23
	s_add_u32 s30, s26, 0x100
	s_addc_u32 s31, s27, 0
	s_add_u32 s28, s52, s22
	s_addc_u32 s29, s53, s23
	s_add_u32 s26, s26, 0x180
	s_addc_u32 s27, s27, 0
	s_cmpk_eq_i32 s22, 0x1f00
	s_cselect_b32 s27, s51, s27
	s_cselect_b32 s26, s50, s26
	s_cselect_b32 s29, s21, s29
	s_cselect_b32 s28, s20, s28
	s_cselect_b32 s31, s19, s31
	s_cselect_b32 s30, s18, s30
	s_mov_b32 m0, s37
	v_lshl_add_u64 v[210:211], v[148:149], 0, s[22:23]
	ds_read_b128 v[198:201], v154
	ds_read_b128 v[202:205], v154 offset:1024
	ds_read_b128 v[206:209], v154 offset:2048
	ds_read_b128 v[214:217], v154 offset:3072
	ds_read_b128 v[218:221], v154 offset:4096
	ds_read_b128 v[222:225], v154 offset:5120
	ds_read_b128 v[226:229], v154 offset:6144
	ds_read_b128 v[230:233], v154 offset:7168
	global_load_lds_dwordx4 v[210:211], off
	v_lshl_add_u64 v[210:211], v[150:151], 0, s[22:23]
	s_mov_b32 m0, s38
	s_nop 0
	global_load_lds_dwordx4 v[210:211], off
	s_waitcnt vmcnt(8)
	s_waitcnt lgkmcnt(0)
	s_barrier
	s_setprio 1
	s_waitcnt lgkmcnt(0)
	v_mfma_f32_16x16x32_bf16 v[126:129], v[166:169], v[198:201], v[126:129]
	v_mfma_f32_16x16x32_bf16 v[126:129], v[170:173], v[202:205], v[126:129]
	v_mfma_f32_16x16x32_bf16 v[122:125], v[178:181], v[202:205], v[122:125]
	v_mfma_f32_16x16x32_bf16 v[122:125], v[174:177], v[198:201], v[122:125]
	v_mfma_f32_16x16x32_bf16 v[106:109], v[174:177], v[206:209], v[106:109]
	v_mfma_f32_16x16x32_bf16 v[106:109], v[178:181], v[214:217], v[106:109]
	v_mfma_f32_16x16x32_bf16 v[110:113], v[170:173], v[214:217], v[110:113]
	v_mfma_f32_16x16x32_bf16 v[110:113], v[166:169], v[206:209], v[110:113]
	v_mfma_f32_16x16x32_bf16 v[94:97], v[166:169], v[218:221], v[94:97]
	v_mfma_f32_16x16x32_bf16 v[94:97], v[170:173], v[222:225], v[94:97]
	v_mfma_f32_16x16x32_bf16 v[90:93], v[178:181], v[222:225], v[90:93]
	v_mfma_f32_16x16x32_bf16 v[90:93], v[174:177], v[218:221], v[90:93]
	v_mfma_f32_16x16x32_bf16 v[74:77], v[174:177], v[226:229], v[74:77]
	v_mfma_f32_16x16x32_bf16 v[74:77], v[178:181], v[230:233], v[74:77]
	v_mfma_f32_16x16x32_bf16 v[78:81], v[170:173], v[230:233], v[78:81]
	v_mfma_f32_16x16x32_bf16 v[78:81], v[166:169], v[226:229], v[78:81]
	s_setprio 0
	s_setprio 1
	v_mfma_f32_16x16x32_bf16 v[118:121], v[182:185], v[198:201], v[118:121]
	v_mfma_f32_16x16x32_bf16 v[118:121], v[186:189], v[202:205], v[118:121]
	v_mfma_f32_16x16x32_bf16 v[114:117], v[194:197], v[202:205], v[114:117]
	v_mfma_f32_16x16x32_bf16 v[114:117], v[190:193], v[198:201], v[114:117]
	v_mfma_f32_16x16x32_bf16 v[98:101], v[190:193], v[206:209], v[98:101]
	v_mfma_f32_16x16x32_bf16 v[98:101], v[194:197], v[214:217], v[98:101]
	v_mfma_f32_16x16x32_bf16 v[102:105], v[186:189], v[214:217], v[102:105]
	v_mfma_f32_16x16x32_bf16 v[102:105], v[182:185], v[206:209], v[102:105]
	v_mfma_f32_16x16x32_bf16 v[86:89], v[182:185], v[218:221], v[86:89]
	v_mfma_f32_16x16x32_bf16 v[86:89], v[186:189], v[222:225], v[86:89]
	v_mfma_f32_16x16x32_bf16 v[82:85], v[194:197], v[222:225], v[82:85]
	v_mfma_f32_16x16x32_bf16 v[82:85], v[190:193], v[218:221], v[82:85]
	v_mfma_f32_16x16x32_bf16 v[66:69], v[190:193], v[226:229], v[66:69]
	v_mfma_f32_16x16x32_bf16 v[66:69], v[194:197], v[230:233], v[66:69]
	v_mfma_f32_16x16x32_bf16 v[70:73], v[186:189], v[230:233], v[70:73]
	v_mfma_f32_16x16x32_bf16 v[70:73], v[182:185], v[226:229], v[70:73]
	s_setprio 0
	s_barrier
	s_mov_b32 m0, s39
	v_lshl_add_u64 v[210:211], s[28:29], 0, v[132:133]
	s_add_u32 s56, s28, 0x108000
	ds_read_b128 v[198:201], v154 offset:16384
	ds_read_b128 v[202:205], v154 offset:17408
	ds_read_b128 v[206:209], v154 offset:18432
	ds_read_b128 v[214:217], v154 offset:19456
	ds_read_b128 v[218:221], v154 offset:20480
	ds_read_b128 v[222:225], v154 offset:21504
	ds_read_b128 v[226:229], v154 offset:22528
	ds_read_b128 v[230:233], v154 offset:23552
	global_load_lds_dwordx4 v[210:211], off
	v_lshl_add_u64 v[234:235], s[28:29], 0, v[136:137]
	s_mov_b32 m0, s40
	s_addc_u32 s57, s29, 0
	global_load_lds_dwordx4 v[234:235], off
	v_lshl_add_u64 v[236:237], s[56:57], 0, v[132:133]
	s_mov_b32 m0, s41
	s_nop 0
	global_load_lds_dwordx4 v[236:237], off
	v_lshl_add_u64 v[236:237], s[56:57], 0, v[136:137]
	s_mov_b32 m0, s42
	s_nop 0
	global_load_lds_dwordx4 v[236:237], off
	v_lshl_add_u64 v[236:237], s[30:31], 0, v[130:131]
	s_mov_b32 m0, s2
	s_nop 0
	global_load_lds_dwordx4 v[236:237], off
	v_lshl_add_u64 v[236:237], s[30:31], 0, v[134:135]
	s_mov_b32 m0, s3
	s_nop 0
	global_load_lds_dwordx4 v[236:237], off
	s_waitcnt vmcnt(8)
	s_waitcnt lgkmcnt(0)
	s_barrier
	s_setprio 1
	s_waitcnt lgkmcnt(0)
	v_mfma_f32_16x16x32_bf16 v[62:65], v[166:169], v[198:201], v[62:65]
	v_mfma_f32_16x16x32_bf16 v[62:65], v[170:173], v[202:205], v[62:65]
	v_mfma_f32_16x16x32_bf16 v[58:61], v[178:181], v[202:205], v[58:61]
	v_mfma_f32_16x16x32_bf16 v[58:61], v[174:177], v[198:201], v[58:61]
	v_mfma_f32_16x16x32_bf16 v[42:45], v[174:177], v[206:209], v[42:45]
	v_mfma_f32_16x16x32_bf16 v[42:45], v[178:181], v[214:217], v[42:45]
	v_mfma_f32_16x16x32_bf16 v[46:49], v[170:173], v[214:217], v[46:49]
	v_mfma_f32_16x16x32_bf16 v[46:49], v[166:169], v[206:209], v[46:49]
	v_mfma_f32_16x16x32_bf16 v[30:33], v[166:169], v[218:221], v[30:33]
	v_mfma_f32_16x16x32_bf16 v[30:33], v[170:173], v[222:225], v[30:33]
	v_mfma_f32_16x16x32_bf16 v[26:29], v[178:181], v[222:225], v[26:29]
	v_mfma_f32_16x16x32_bf16 v[26:29], v[174:177], v[218:221], v[26:29]
	v_mfma_f32_16x16x32_bf16 v[10:13], v[174:177], v[226:229], v[10:13]
	v_mfma_f32_16x16x32_bf16 v[10:13], v[178:181], v[230:233], v[10:13]
	v_mfma_f32_16x16x32_bf16 v[14:17], v[170:173], v[230:233], v[14:17]
	v_mfma_f32_16x16x32_bf16 v[14:17], v[166:169], v[226:229], v[14:17]
	s_setprio 0
	s_setprio 1
	v_mfma_f32_16x16x32_bf16 v[54:57], v[182:185], v[198:201], v[54:57]
	v_mfma_f32_16x16x32_bf16 v[54:57], v[186:189], v[202:205], v[54:57]
	v_mfma_f32_16x16x32_bf16 v[50:53], v[194:197], v[202:205], v[50:53]
	v_mfma_f32_16x16x32_bf16 v[50:53], v[190:193], v[198:201], v[50:53]
	v_mfma_f32_16x16x32_bf16 v[34:37], v[190:193], v[206:209], v[34:37]
	v_mfma_f32_16x16x32_bf16 v[34:37], v[194:197], v[214:217], v[34:37]
	v_mfma_f32_16x16x32_bf16 v[38:41], v[186:189], v[214:217], v[38:41]
	v_mfma_f32_16x16x32_bf16 v[38:41], v[182:185], v[206:209], v[38:41]
	v_mfma_f32_16x16x32_bf16 v[22:25], v[182:185], v[218:221], v[22:25]
	v_mfma_f32_16x16x32_bf16 v[22:25], v[186:189], v[222:225], v[22:25]
	v_mfma_f32_16x16x32_bf16 v[18:21], v[194:197], v[222:225], v[18:21]
	v_mfma_f32_16x16x32_bf16 v[18:21], v[190:193], v[218:221], v[18:21]
	v_mfma_f32_16x16x32_bf16 v[2:5], v[190:193], v[226:229], v[2:5]
	v_mfma_f32_16x16x32_bf16 v[2:5], v[194:197], v[230:233], v[2:5]
	v_mfma_f32_16x16x32_bf16 v[6:9], v[186:189], v[230:233], v[6:9]
	v_mfma_f32_16x16x32_bf16 v[6:9], v[182:185], v[226:229], v[6:9]
	s_setprio 0
	s_barrier
	ds_read_b128 v[166:169], v156
	ds_read_b128 v[170:173], v156 offset:1024
	ds_read_b128 v[174:177], v156 offset:2048
	ds_read_b128 v[178:181], v156 offset:3072
	ds_read_b128 v[182:185], v157
	ds_read_b128 v[186:189], v157 offset:1024
	ds_read_b128 v[190:193], v157 offset:2048
	ds_read_b128 v[194:197], v157 offset:3072
	s_add_u32 s30, s30, 0x108000
	s_addc_u32 s31, s31, 0
	s_mov_b32 m0, s33
	v_lshl_add_u64 v[236:237], s[30:31], 0, v[130:131]
	ds_read_b128 v[198:201], v154 offset:32768
	ds_read_b128 v[202:205], v154 offset:33792
	ds_read_b128 v[206:209], v154 offset:34816
	ds_read_b128 v[214:217], v154 offset:35840
	ds_read_b128 v[218:221], v154 offset:36864
	ds_read_b128 v[222:225], v154 offset:37888
	ds_read_b128 v[226:229], v154 offset:38912
	ds_read_b128 v[230:233], v154 offset:39936
	global_load_lds_dwordx4 v[236:237], off
	v_lshl_add_u64 v[236:237], s[30:31], 0, v[134:135]
	s_mov_b32 m0, s34
	s_nop 0
	global_load_lds_dwordx4 v[236:237], off
	s_waitcnt vmcnt(8)
	s_waitcnt lgkmcnt(0)
	s_barrier
	s_setprio 1
	s_waitcnt lgkmcnt(0)
	v_mfma_f32_16x16x32_bf16 v[126:129], v[166:169], v[198:201], v[126:129]
	v_mfma_f32_16x16x32_bf16 v[126:129], v[170:173], v[202:205], v[126:129]
	v_mfma_f32_16x16x32_bf16 v[122:125], v[178:181], v[202:205], v[122:125]
	v_mfma_f32_16x16x32_bf16 v[122:125], v[174:177], v[198:201], v[122:125]
	v_mfma_f32_16x16x32_bf16 v[106:109], v[174:177], v[206:209], v[106:109]
	v_mfma_f32_16x16x32_bf16 v[106:109], v[178:181], v[214:217], v[106:109]
	v_mfma_f32_16x16x32_bf16 v[110:113], v[170:173], v[214:217], v[110:113]
	v_mfma_f32_16x16x32_bf16 v[110:113], v[166:169], v[206:209], v[110:113]
	v_mfma_f32_16x16x32_bf16 v[94:97], v[166:169], v[218:221], v[94:97]
	v_mfma_f32_16x16x32_bf16 v[94:97], v[170:173], v[222:225], v[94:97]
	v_mfma_f32_16x16x32_bf16 v[90:93], v[178:181], v[222:225], v[90:93]
	v_mfma_f32_16x16x32_bf16 v[90:93], v[174:177], v[218:221], v[90:93]
	v_mfma_f32_16x16x32_bf16 v[74:77], v[174:177], v[226:229], v[74:77]
	v_mfma_f32_16x16x32_bf16 v[74:77], v[178:181], v[230:233], v[74:77]
	v_mfma_f32_16x16x32_bf16 v[78:81], v[170:173], v[230:233], v[78:81]
	v_mfma_f32_16x16x32_bf16 v[78:81], v[166:169], v[226:229], v[78:81]
	s_setprio 0
	s_setprio 1
	v_mfma_f32_16x16x32_bf16 v[118:121], v[182:185], v[198:201], v[118:121]
	v_mfma_f32_16x16x32_bf16 v[118:121], v[186:189], v[202:205], v[118:121]
	v_mfma_f32_16x16x32_bf16 v[114:117], v[194:197], v[202:205], v[114:117]
	v_mfma_f32_16x16x32_bf16 v[114:117], v[190:193], v[198:201], v[114:117]
	v_mfma_f32_16x16x32_bf16 v[98:101], v[190:193], v[206:209], v[98:101]
	v_mfma_f32_16x16x32_bf16 v[98:101], v[194:197], v[214:217], v[98:101]
	v_mfma_f32_16x16x32_bf16 v[102:105], v[186:189], v[214:217], v[102:105]
	v_mfma_f32_16x16x32_bf16 v[102:105], v[182:185], v[206:209], v[102:105]
	v_mfma_f32_16x16x32_bf16 v[86:89], v[182:185], v[218:221], v[86:89]
	v_mfma_f32_16x16x32_bf16 v[86:89], v[186:189], v[222:225], v[86:89]
	v_mfma_f32_16x16x32_bf16 v[82:85], v[194:197], v[222:225], v[82:85]
	v_mfma_f32_16x16x32_bf16 v[82:85], v[190:193], v[218:221], v[82:85]
	v_mfma_f32_16x16x32_bf16 v[66:69], v[190:193], v[226:229], v[66:69]
	v_mfma_f32_16x16x32_bf16 v[66:69], v[194:197], v[230:233], v[66:69]
	v_mfma_f32_16x16x32_bf16 v[70:73], v[186:189], v[230:233], v[70:73]
	v_mfma_f32_16x16x32_bf16 v[70:73], v[182:185], v[226:229], v[70:73]
	s_setprio 0
	s_barrier
	s_mov_b32 m0, s43
	v_lshl_add_u64 v[210:211], v[210:211], 0, s[14:15]
	s_add_u32 s28, s28, 0x108080
	ds_read_b128 v[198:201], v154 offset:49152
	ds_read_b128 v[202:205], v154 offset:50176
	ds_read_b128 v[206:209], v154 offset:51200
	ds_read_b128 v[214:217], v154 offset:52224
	ds_read_b128 v[218:221], v154 offset:53248
	ds_read_b128 v[222:225], v154 offset:54272
	ds_read_b128 v[226:229], v154 offset:55296
	ds_read_b128 v[230:233], v154 offset:56320
	global_load_lds_dwordx4 v[210:211], off
	v_lshl_add_u64 v[210:211], v[234:235], 0, s[14:15]
	s_mov_b32 m0, s44
	s_addc_u32 s29, s29, 0
	global_load_lds_dwordx4 v[210:211], off
	v_lshl_add_u64 v[210:211], s[28:29], 0, v[132:133]
	s_mov_b32 m0, s45
	s_nop 0
	global_load_lds_dwordx4 v[210:211], off
	v_lshl_add_u64 v[210:211], s[28:29], 0, v[136:137]
	s_mov_b32 m0, s46
	s_nop 0
	global_load_lds_dwordx4 v[210:211], off
	v_lshl_add_u64 v[210:211], s[26:27], 0, v[130:131]
	s_mov_b32 m0, s35
	s_nop 0
	global_load_lds_dwordx4 v[210:211], off
	v_lshl_add_u64 v[210:211], s[26:27], 0, v[134:135]
	s_mov_b32 m0, s36
	s_nop 0
	global_load_lds_dwordx4 v[210:211], off
	s_waitcnt vmcnt(8)
	s_waitcnt lgkmcnt(0)
	s_barrier
	s_setprio 1
	s_waitcnt lgkmcnt(0)
	v_mfma_f32_16x16x32_bf16 v[62:65], v[166:169], v[198:201], v[62:65]
	v_mfma_f32_16x16x32_bf16 v[62:65], v[170:173], v[202:205], v[62:65]
	v_mfma_f32_16x16x32_bf16 v[58:61], v[178:181], v[202:205], v[58:61]
	v_mfma_f32_16x16x32_bf16 v[58:61], v[174:177], v[198:201], v[58:61]
	v_mfma_f32_16x16x32_bf16 v[42:45], v[174:177], v[206:209], v[42:45]
	v_mfma_f32_16x16x32_bf16 v[42:45], v[178:181], v[214:217], v[42:45]
	v_mfma_f32_16x16x32_bf16 v[46:49], v[170:173], v[214:217], v[46:49]
	v_mfma_f32_16x16x32_bf16 v[46:49], v[166:169], v[206:209], v[46:49]
	v_mfma_f32_16x16x32_bf16 v[30:33], v[166:169], v[218:221], v[30:33]
	v_mfma_f32_16x16x32_bf16 v[30:33], v[170:173], v[222:225], v[30:33]
	v_mfma_f32_16x16x32_bf16 v[26:29], v[178:181], v[222:225], v[26:29]
	v_mfma_f32_16x16x32_bf16 v[26:29], v[174:177], v[218:221], v[26:29]
	v_mfma_f32_16x16x32_bf16 v[10:13], v[174:177], v[226:229], v[10:13]
	v_mfma_f32_16x16x32_bf16 v[10:13], v[178:181], v[230:233], v[10:13]
	v_mfma_f32_16x16x32_bf16 v[14:17], v[170:173], v[230:233], v[14:17]
	v_mfma_f32_16x16x32_bf16 v[14:17], v[166:169], v[226:229], v[14:17]
	s_setprio 0
	s_setprio 1
	v_mfma_f32_16x16x32_bf16 v[54:57], v[182:185], v[198:201], v[54:57]
	v_mfma_f32_16x16x32_bf16 v[54:57], v[186:189], v[202:205], v[54:57]
	v_mfma_f32_16x16x32_bf16 v[50:53], v[194:197], v[202:205], v[50:53]
	v_mfma_f32_16x16x32_bf16 v[50:53], v[190:193], v[198:201], v[50:53]
	v_mfma_f32_16x16x32_bf16 v[34:37], v[190:193], v[206:209], v[34:37]
	v_mfma_f32_16x16x32_bf16 v[34:37], v[194:197], v[214:217], v[34:37]
	v_mfma_f32_16x16x32_bf16 v[38:41], v[186:189], v[214:217], v[38:41]
	v_mfma_f32_16x16x32_bf16 v[38:41], v[182:185], v[206:209], v[38:41]
	v_mfma_f32_16x16x32_bf16 v[22:25], v[182:185], v[218:221], v[22:25]
	v_mfma_f32_16x16x32_bf16 v[22:25], v[186:189], v[222:225], v[22:25]
	v_mfma_f32_16x16x32_bf16 v[18:21], v[194:197], v[222:225], v[18:21]
	v_mfma_f32_16x16x32_bf16 v[18:21], v[190:193], v[218:221], v[18:21]
	v_mfma_f32_16x16x32_bf16 v[2:5], v[190:193], v[226:229], v[2:5]
	v_mfma_f32_16x16x32_bf16 v[2:5], v[194:197], v[230:233], v[2:5]
	v_mfma_f32_16x16x32_bf16 v[6:9], v[186:189], v[230:233], v[6:9]
	v_mfma_f32_16x16x32_bf16 v[6:9], v[182:185], v[226:229], v[6:9]
	s_setprio 0
	s_barrier
	s_add_i32 s54, s54, 2
	s_add_u32 s22, s22, 0x100
	s_addc_u32 s23, s23, 0
	s_cmp_gt_u32 s54, 61
	s_cbranch_scc0 .LBB0_612
	s_and_b64 vcc, exec, s[16:17]
	s_cbranch_vccz .LBB0_615
	s_barrier

.LBB0_844:
	s_add_i32 s35, s52, 0xfffe8000
	s_and_b32 s34, s30, 0x100
	s_and_b32 s35, s35, 0x3e0000
	s_or_b32 s34, s34, s35
	s_add_u32 s53, s28, s34
	s_addc_u32 s55, s29, 0
	s_add_u32 s34, s30, 0x100
	s_addc_u32 s35, s31, 0
	s_add_i32 s37, s52, 0xffff8000
	s_and_b32 s36, s34, 0x100
	s_and_b32 s37, s37, 0x7e0000
	s_or_b32 s36, s37, s36
	s_add_u32 s36, s28, s36
	s_addc_u32 s37, s29, 0
	s_add_u32 s54, s49, s30
	s_addc_u32 s31, s50, s31
	s_add_i32 s38, s30, 0x180
	s_and_b32 s38, s38, 0x180
	s_and_b32 s39, s52, 0x7e0000
	s_or_b32 s38, s39, s38
	s_add_u32 s56, s28, s38
	s_addc_u32 s57, s29, 0
	s_cmpk_eq_i32 s30, 0x3f00
	s_cselect_b32 s39, s1, s37
	s_cselect_b32 s38, s21, s36
	s_cselect_b32 s37, s23, s31
	s_cselect_b32 s36, s22, s54
	s_cselect_b32 s31, s48, s57
	s_cselect_b32 s30, s27, s56
	s_add_i32 s56, 0, 0x10000
	v_add_u32_e32 v124, s56, v211
	ds_read_b128 v[104:107], v124
	ds_read_b128 v[108:111], v124 offset:1024
	ds_read_b128 v[120:123], v124 offset:2048
	ds_read_b128 v[124:127], v124 offset:3072
	ds_read_b128 v[144:147], v214
	ds_read_b128 v[148:151], v214 offset:1024
	ds_read_b128 v[152:155], v214 offset:2048
	ds_read_b128 v[156:159], v214 offset:3072
	s_add_u32 s54, s53, 0x10080
	s_addc_u32 s55, s55, 0
	v_lshl_add_u64 v[200:201], s[54:55], 0, v[184:185]
	s_add_i32 m0, s3, 0xc000
	ds_read_b128 v[160:163], v215
	ds_read_b128 v[164:167], v215 offset:1024
	ds_read_b128 v[168:171], v215 offset:2048
	ds_read_b128 v[172:175], v215 offset:3072
	ds_read_b128 v[176:179], v215 offset:4096
	ds_read_b128 v[180:183], v215 offset:5120
	ds_read_b128 v[192:195], v215 offset:6144
	ds_read_b128 v[196:199], v215 offset:7168
	global_load_lds_dwordx4 v[200:201], off
	v_lshl_add_u64 v[200:201], s[54:55], 0, v[188:189]
	s_add_i32 m0, s3, 0xe000
	s_nop 0
	global_load_lds_dwordx4 v[200:201], off
	s_waitcnt vmcnt(8)
	s_waitcnt lgkmcnt(0)
	s_barrier
	s_setprio 1
	s_waitcnt lgkmcnt(0)
	v_mfma_f32_16x16x32_bf16 v[140:143], v[104:107], v[160:163], v[140:143]
	v_mfma_f32_16x16x32_bf16 v[140:143], v[108:111], v[164:167], v[140:143]
	v_mfma_f32_16x16x32_bf16 v[136:139], v[124:127], v[164:167], v[136:139]
	v_mfma_f32_16x16x32_bf16 v[136:139], v[120:123], v[160:163], v[136:139]
	v_mfma_f32_16x16x32_bf16 v[112:115], v[120:123], v[168:171], v[112:115]
	v_mfma_f32_16x16x32_bf16 v[112:115], v[124:127], v[172:175], v[112:115]
	v_mfma_f32_16x16x32_bf16 v[116:119], v[108:111], v[172:175], v[116:119]
	v_mfma_f32_16x16x32_bf16 v[116:119], v[104:107], v[168:171], v[116:119]
	v_mfma_f32_16x16x32_bf16 v[92:95], v[104:107], v[176:179], v[92:95]
	v_mfma_f32_16x16x32_bf16 v[92:95], v[108:111], v[180:183], v[92:95]
	v_mfma_f32_16x16x32_bf16 v[88:91], v[124:127], v[180:183], v[88:91]
	v_mfma_f32_16x16x32_bf16 v[88:91], v[120:123], v[176:179], v[88:91]
	v_mfma_f32_16x16x32_bf16 v[72:75], v[120:123], v[192:195], v[72:75]
	v_mfma_f32_16x16x32_bf16 v[72:75], v[124:127], v[196:199], v[72:75]
	v_mfma_f32_16x16x32_bf16 v[76:79], v[108:111], v[196:199], v[76:79]
	v_mfma_f32_16x16x32_bf16 v[76:79], v[104:107], v[192:195], v[76:79]
	s_setprio 0
	s_setprio 1
	v_mfma_f32_16x16x32_bf16 v[132:135], v[144:147], v[160:163], v[132:135]
	v_mfma_f32_16x16x32_bf16 v[132:135], v[148:151], v[164:167], v[132:135]
	v_mfma_f32_16x16x32_bf16 v[128:131], v[156:159], v[164:167], v[128:131]
	v_mfma_f32_16x16x32_bf16 v[128:131], v[152:155], v[160:163], v[128:131]
	v_mfma_f32_16x16x32_bf16 v[96:99], v[152:155], v[168:171], v[96:99]
	v_mfma_f32_16x16x32_bf16 v[96:99], v[156:159], v[172:175], v[96:99]
	v_mfma_f32_16x16x32_bf16 v[100:103], v[148:151], v[172:175], v[100:103]
	v_mfma_f32_16x16x32_bf16 v[100:103], v[144:147], v[168:171], v[100:103]
	v_mfma_f32_16x16x32_bf16 v[84:87], v[144:147], v[176:179], v[84:87]
	v_mfma_f32_16x16x32_bf16 v[84:87], v[148:151], v[180:183], v[84:87]
	v_mfma_f32_16x16x32_bf16 v[80:83], v[156:159], v[180:183], v[80:83]
	v_mfma_f32_16x16x32_bf16 v[80:83], v[152:155], v[176:179], v[80:83]
	v_mfma_f32_16x16x32_bf16 v[64:67], v[152:155], v[192:195], v[64:67]
	v_mfma_f32_16x16x32_bf16 v[64:67], v[156:159], v[196:199], v[64:67]
	v_mfma_f32_16x16x32_bf16 v[68:71], v[148:151], v[196:199], v[68:71]
	v_mfma_f32_16x16x32_bf16 v[68:71], v[144:147], v[192:195], v[68:71]
	s_setprio 0
	s_barrier
	s_add_i32 s53, s56, s2
	v_lshl_add_u64 v[200:201], s[36:37], 0, v[186:187]
	s_mov_b32 m0, s53
	ds_read_b128 v[160:163], v215 offset:16384
	ds_read_b128 v[164:167], v215 offset:17408
	ds_read_b128 v[168:171], v215 offset:18432
	ds_read_b128 v[172:175], v215 offset:19456
	ds_read_b128 v[176:179], v215 offset:20480
	ds_read_b128 v[180:183], v215 offset:21504
	ds_read_b128 v[192:195], v215 offset:22528
	ds_read_b128 v[196:199], v215 offset:23552
	global_load_lds_dwordx4 v[200:201], off
	s_add_i32 m0, s53, 0x2000
	s_add_u32 s54, s36, 0x208000
	v_lshl_add_u64 v[202:203], s[36:37], 0, v[190:191]
	s_addc_u32 s55, s37, 0
	s_add_i32 s53, s45, s2
	global_load_lds_dwordx4 v[202:203], off
	v_lshl_add_u64 v[204:205], s[54:55], 0, v[186:187]
	s_mov_b32 m0, s53
	s_nop 0
	global_load_lds_dwordx4 v[204:205], off
	v_lshl_add_u64 v[204:205], s[54:55], 0, v[190:191]
	s_add_i32 m0, s53, 0x2000
	s_nop 0
	global_load_lds_dwordx4 v[204:205], off
	v_lshl_add_u64 v[204:205], s[38:39], 0, v[184:185]
	s_mov_b32 m0, s3
	s_nop 0
	global_load_lds_dwordx4 v[204:205], off
	v_lshl_add_u64 v[204:205], s[38:39], 0, v[188:189]
	s_mov_b32 m0, s33
	s_nop 0
	global_load_lds_dwordx4 v[204:205], off
	s_waitcnt vmcnt(8)
	s_waitcnt lgkmcnt(0)
	s_barrier
	s_setprio 1
	s_waitcnt lgkmcnt(0)
	v_mfma_f32_16x16x32_bf16 v[60:63], v[104:107], v[160:163], v[60:63]
	v_mfma_f32_16x16x32_bf16 v[60:63], v[108:111], v[164:167], v[60:63]
	v_mfma_f32_16x16x32_bf16 v[56:59], v[124:127], v[164:167], v[56:59]
	v_mfma_f32_16x16x32_bf16 v[56:59], v[120:123], v[160:163], v[56:59]
	v_mfma_f32_16x16x32_bf16 v[40:43], v[120:123], v[168:171], v[40:43]
	v_mfma_f32_16x16x32_bf16 v[40:43], v[124:127], v[172:175], v[40:43]
	v_mfma_f32_16x16x32_bf16 v[44:47], v[108:111], v[172:175], v[44:47]
	v_mfma_f32_16x16x32_bf16 v[44:47], v[104:107], v[168:171], v[44:47]
	v_mfma_f32_16x16x32_bf16 v[28:31], v[104:107], v[176:179], v[28:31]
	v_mfma_f32_16x16x32_bf16 v[28:31], v[108:111], v[180:183], v[28:31]
	v_mfma_f32_16x16x32_bf16 v[24:27], v[124:127], v[180:183], v[24:27]
	v_mfma_f32_16x16x32_bf16 v[24:27], v[120:123], v[176:179], v[24:27]
	v_mfma_f32_16x16x32_bf16 v[8:11], v[120:123], v[192:195], v[8:11]
	v_mfma_f32_16x16x32_bf16 v[8:11], v[124:127], v[196:199], v[8:11]
	v_mfma_f32_16x16x32_bf16 v[12:15], v[108:111], v[196:199], v[12:15]
	v_mfma_f32_16x16x32_bf16 v[12:15], v[104:107], v[192:195], v[12:15]
	s_setprio 0
	s_setprio 1
	v_mfma_f32_16x16x32_bf16 v[52:55], v[144:147], v[160:163], v[52:55]
	v_mfma_f32_16x16x32_bf16 v[52:55], v[148:151], v[164:167], v[52:55]
	v_mfma_f32_16x16x32_bf16 v[48:51], v[156:159], v[164:167], v[48:51]
	v_mfma_f32_16x16x32_bf16 v[48:51], v[152:155], v[160:163], v[48:51]
	v_mfma_f32_16x16x32_bf16 v[32:35], v[152:155], v[168:171], v[32:35]
	v_mfma_f32_16x16x32_bf16 v[32:35], v[156:159], v[172:175], v[32:35]
	v_mfma_f32_16x16x32_bf16 v[36:39], v[148:151], v[172:175], v[36:39]
	v_mfma_f32_16x16x32_bf16 v[36:39], v[144:147], v[168:171], v[36:39]
	v_mfma_f32_16x16x32_bf16 v[20:23], v[144:147], v[176:179], v[20:23]
	v_mfma_f32_16x16x32_bf16 v[20:23], v[148:151], v[180:183], v[20:23]
	v_mfma_f32_16x16x32_bf16 v[16:19], v[156:159], v[180:183], v[16:19]
	v_mfma_f32_16x16x32_bf16 v[16:19], v[152:155], v[176:179], v[16:19]
	v_mfma_f32_16x16x32_bf16 v[0:3], v[152:155], v[192:195], v[0:3]
	v_mfma_f32_16x16x32_bf16 v[0:3], v[156:159], v[196:199], v[0:3]
	v_mfma_f32_16x16x32_bf16 v[4:7], v[148:151], v[196:199], v[4:7]
	v_mfma_f32_16x16x32_bf16 v[4:7], v[144:147], v[192:195], v[4:7]
	s_setprio 0
	s_barrier
	s_add_i32 s53, 0, 0x18000
	s_add_i32 s54, 0, 0x1c000
	v_add_u32_e32 v124, s53, v211
	v_add_u32_e32 v156, s54, v211
	ds_read_b128 v[104:107], v124
	ds_read_b128 v[108:111], v124 offset:1024
	ds_read_b128 v[120:123], v124 offset:2048
	ds_read_b128 v[124:127], v124 offset:3072
	ds_read_b128 v[144:147], v156
	ds_read_b128 v[148:151], v156 offset:1024
	ds_read_b128 v[152:155], v156 offset:2048
	ds_read_b128 v[156:159], v156 offset:3072
	s_add_u32 s38, s38, 0x10000
	s_addc_u32 s39, s39, 0
	s_mov_b32 m0, s40
	v_lshl_add_u64 v[204:205], s[38:39], 0, v[184:185]
	ds_read_b128 v[160:163], v215 offset:32768
	ds_read_b128 v[164:167], v215 offset:33792
	ds_read_b128 v[168:171], v215 offset:34816
	ds_read_b128 v[172:175], v215 offset:35840
	ds_read_b128 v[176:179], v215 offset:36864
	ds_read_b128 v[180:183], v215 offset:37888
	ds_read_b128 v[192:195], v215 offset:38912
	ds_read_b128 v[196:199], v215 offset:39936
	global_load_lds_dwordx4 v[204:205], off
	v_lshl_add_u64 v[204:205], s[38:39], 0, v[188:189]
	s_mov_b32 m0, s41
	s_nop 0
	global_load_lds_dwordx4 v[204:205], off
	s_waitcnt vmcnt(8)
	s_waitcnt lgkmcnt(0)
	s_barrier
	s_setprio 1
	s_waitcnt lgkmcnt(0)
	v_mfma_f32_16x16x32_bf16 v[140:143], v[104:107], v[160:163], v[140:143]
	v_mfma_f32_16x16x32_bf16 v[140:143], v[108:111], v[164:167], v[140:143]
	v_mfma_f32_16x16x32_bf16 v[136:139], v[124:127], v[164:167], v[136:139]
	v_mfma_f32_16x16x32_bf16 v[136:139], v[120:123], v[160:163], v[136:139]
	v_mfma_f32_16x16x32_bf16 v[112:115], v[120:123], v[168:171], v[112:115]
	v_mfma_f32_16x16x32_bf16 v[112:115], v[124:127], v[172:175], v[112:115]
	v_mfma_f32_16x16x32_bf16 v[116:119], v[108:111], v[172:175], v[116:119]
	v_mfma_f32_16x16x32_bf16 v[116:119], v[104:107], v[168:171], v[116:119]
	v_mfma_f32_16x16x32_bf16 v[92:95], v[104:107], v[176:179], v[92:95]
	v_mfma_f32_16x16x32_bf16 v[92:95], v[108:111], v[180:183], v[92:95]
	v_mfma_f32_16x16x32_bf16 v[88:91], v[124:127], v[180:183], v[88:91]
	v_mfma_f32_16x16x32_bf16 v[88:91], v[120:123], v[176:179], v[88:91]
	v_mfma_f32_16x16x32_bf16 v[72:75], v[120:123], v[192:195], v[72:75]
	v_mfma_f32_16x16x32_bf16 v[72:75], v[124:127], v[196:199], v[72:75]
	v_mfma_f32_16x16x32_bf16 v[76:79], v[108:111], v[196:199], v[76:79]
	v_mfma_f32_16x16x32_bf16 v[76:79], v[104:107], v[192:195], v[76:79]
	s_setprio 0
	s_setprio 1
	v_mfma_f32_16x16x32_bf16 v[132:135], v[144:147], v[160:163], v[132:135]
	v_mfma_f32_16x16x32_bf16 v[132:135], v[148:151], v[164:167], v[132:135]
	v_mfma_f32_16x16x32_bf16 v[128:131], v[156:159], v[164:167], v[128:131]
	v_mfma_f32_16x16x32_bf16 v[128:131], v[152:155], v[160:163], v[128:131]
	v_mfma_f32_16x16x32_bf16 v[96:99], v[152:155], v[168:171], v[96:99]
	v_mfma_f32_16x16x32_bf16 v[96:99], v[156:159], v[172:175], v[96:99]
	v_mfma_f32_16x16x32_bf16 v[100:103], v[148:151], v[172:175], v[100:103]
	v_mfma_f32_16x16x32_bf16 v[100:103], v[144:147], v[168:171], v[100:103]
	v_mfma_f32_16x16x32_bf16 v[84:87], v[144:147], v[176:179], v[84:87]
	v_mfma_f32_16x16x32_bf16 v[84:87], v[148:151], v[180:183], v[84:87]
	v_mfma_f32_16x16x32_bf16 v[80:83], v[156:159], v[180:183], v[80:83]
	v_mfma_f32_16x16x32_bf16 v[80:83], v[152:155], v[176:179], v[80:83]
	v_mfma_f32_16x16x32_bf16 v[64:67], v[152:155], v[192:195], v[64:67]
	v_mfma_f32_16x16x32_bf16 v[64:67], v[156:159], v[196:199], v[64:67]
	v_mfma_f32_16x16x32_bf16 v[68:71], v[148:151], v[196:199], v[68:71]
	v_mfma_f32_16x16x32_bf16 v[68:71], v[144:147], v[192:195], v[68:71]
	s_setprio 0
	s_barrier
	s_add_i32 s38, s53, s2
	v_lshl_add_u64 v[200:201], v[200:201], 0, s[16:17]
	s_mov_b32 m0, s38
	ds_read_b128 v[160:163], v215 offset:49152
	ds_read_b128 v[164:167], v215 offset:50176
	ds_read_b128 v[168:171], v215 offset:51200
	ds_read_b128 v[172:175], v215 offset:52224
	ds_read_b128 v[176:179], v215 offset:53248
	ds_read_b128 v[180:183], v215 offset:54272
	ds_read_b128 v[192:195], v215 offset:55296
	ds_read_b128 v[196:199], v215 offset:56320
	global_load_lds_dwordx4 v[200:201], off
	s_add_i32 m0, s38, 0x2000
	s_add_u32 s36, s36, 0x208080
	v_lshl_add_u64 v[200:201], v[202:203], 0, s[16:17]
	s_addc_u32 s37, s37, 0
	s_add_i32 s38, s54, s2
	global_load_lds_dwordx4 v[200:201], off
	v_lshl_add_u64 v[200:201], s[36:37], 0, v[186:187]
	s_mov_b32 m0, s38
	s_nop 0
	global_load_lds_dwordx4 v[200:201], off
	v_lshl_add_u64 v[200:201], s[36:37], 0, v[190:191]
	s_add_i32 m0, s38, 0x2000
	s_nop 0
	global_load_lds_dwordx4 v[200:201], off
	v_lshl_add_u64 v[200:201], s[30:31], 0, v[184:185]
	s_mov_b32 m0, s43
	s_nop 0
	global_load_lds_dwordx4 v[200:201], off
	v_lshl_add_u64 v[200:201], s[30:31], 0, v[188:189]
	s_mov_b32 m0, s44
	s_nop 0
	global_load_lds_dwordx4 v[200:201], off
	s_waitcnt vmcnt(8)
	s_waitcnt lgkmcnt(0)
	s_barrier
	s_setprio 1
	s_waitcnt lgkmcnt(0)
	v_mfma_f32_16x16x32_bf16 v[60:63], v[104:107], v[160:163], v[60:63]
	v_mfma_f32_16x16x32_bf16 v[60:63], v[108:111], v[164:167], v[60:63]
	v_mfma_f32_16x16x32_bf16 v[56:59], v[124:127], v[164:167], v[56:59]
	v_mfma_f32_16x16x32_bf16 v[56:59], v[120:123], v[160:163], v[56:59]
	v_mfma_f32_16x16x32_bf16 v[40:43], v[120:123], v[168:171], v[40:43]
	v_mfma_f32_16x16x32_bf16 v[40:43], v[124:127], v[172:175], v[40:43]
	v_mfma_f32_16x16x32_bf16 v[44:47], v[108:111], v[172:175], v[44:47]
	v_mfma_f32_16x16x32_bf16 v[44:47], v[104:107], v[168:171], v[44:47]
	v_mfma_f32_16x16x32_bf16 v[28:31], v[104:107], v[176:179], v[28:31]
	v_mfma_f32_16x16x32_bf16 v[28:31], v[108:111], v[180:183], v[28:31]
	v_mfma_f32_16x16x32_bf16 v[24:27], v[124:127], v[180:183], v[24:27]
	v_mfma_f32_16x16x32_bf16 v[24:27], v[120:123], v[176:179], v[24:27]
	v_mfma_f32_16x16x32_bf16 v[8:11], v[120:123], v[192:195], v[8:11]
	v_mfma_f32_16x16x32_bf16 v[8:11], v[124:127], v[196:199], v[8:11]
	v_mfma_f32_16x16x32_bf16 v[12:15], v[108:111], v[196:199], v[12:15]
	v_mfma_f32_16x16x32_bf16 v[12:15], v[104:107], v[192:195], v[12:15]
	s_setprio 0
	s_setprio 1
	v_mfma_f32_16x16x32_bf16 v[52:55], v[144:147], v[160:163], v[52:55]
	v_mfma_f32_16x16x32_bf16 v[52:55], v[148:151], v[164:167], v[52:55]
	v_mfma_f32_16x16x32_bf16 v[48:51], v[156:159], v[164:167], v[48:51]
	v_mfma_f32_16x16x32_bf16 v[48:51], v[152:155], v[160:163], v[48:51]
	v_mfma_f32_16x16x32_bf16 v[32:35], v[152:155], v[168:171], v[32:35]
	v_mfma_f32_16x16x32_bf16 v[32:35], v[156:159], v[172:175], v[32:35]
	v_mfma_f32_16x16x32_bf16 v[36:39], v[148:151], v[172:175], v[36:39]
	v_mfma_f32_16x16x32_bf16 v[36:39], v[144:147], v[168:171], v[36:39]
	v_mfma_f32_16x16x32_bf16 v[20:23], v[144:147], v[176:179], v[20:23]
	v_mfma_f32_16x16x32_bf16 v[20:23], v[148:151], v[180:183], v[20:23]
	v_mfma_f32_16x16x32_bf16 v[16:19], v[156:159], v[180:183], v[16:19]
	v_mfma_f32_16x16x32_bf16 v[16:19], v[152:155], v[176:179], v[16:19]
	v_mfma_f32_16x16x32_bf16 v[0:3], v[152:155], v[192:195], v[0:3]
	v_mfma_f32_16x16x32_bf16 v[0:3], v[156:159], v[196:199], v[0:3]
	v_mfma_f32_16x16x32_bf16 v[4:7], v[148:151], v[196:199], v[4:7]
	v_mfma_f32_16x16x32_bf16 v[4:7], v[144:147], v[192:195], v[4:7]
	s_setprio 0
	s_barrier
	s_add_i32 s51, s51, 2
	s_add_i32 s52, s52, 0x10000
	s_cmpk_gt_u32 s51, 0x7d
	s_mov_b64 s[30:31], s[34:35]
	s_cbranch_scc0 .LBB0_844
	s_and_b64 vcc, exec, s[18:19]
	s_cbranch_vccz .LBB0_847
	s_barrier
